# K-loop arbitration: the loading wave raises priority before the opening s_barrier of its MFMA segment (already prioritised at release)
# speedup vs baseline: 1.0088x; 1.0047x over previous
; #define PG8_STAGE(bufoff, gbase, voff) do { _Pragma("unroll") for (int _i = 0; _i < 2; ++_i) \
;         __builtin_amdgcn_global_load_lds((const unsigned*)((const char*)(gbase) + (voff)[_i]), (PG8_LAS unsigned*)(lds + (bufoff) + ldsw + _i * 8192), 16, 0, 0); } while (0)
; #define PG8_LDA(dst, b, h) do { _Pragma("unroll") for (int m = 0; m < 4; ++m) _Pragma("unroll") for (int k = 0; k < 2; ++k) dst[m][k] = *(const PG8_LAS bf16x8*)(lds + PG8_SA(b, h) + aoff + m * 2048 + k * 1024); } while (0)
; #define PG8_LDB(dst, b, h) do { _Pragma("unroll") for (int n = 0; n < 2; ++n) _Pragma("unroll") for (int k = 0; k < 2; ++k) dst[n][k] = *(const PG8_LAS bf16x8*)(lds + PG8_SB(b, h) + boff + n * 2048 + k * 1024); } while (0)
; #define PG8_MMA(ai, bj, At, Bt) do { __builtin_amdgcn_s_setprio(1); _Pragma("unroll") for (int m = 0; m < 4; ++m) _Pragma("unroll") for (int n = 0; n < 2; ++n) _Pragma("unroll") for (int k = 0; k < 2; ++k) \
;         acc[ai][bj][m][n] = __builtin_amdgcn_mfma_f32_16x16x32_bf16(Bt[n][k], At[m][k], acc[ai][bj][m][n], 0, 0, 0); __builtin_amdgcn_s_setprio(0); } while (0)
; #define PG8_WAIT_V(n) asm volatile("s_waitcnt vmcnt(" #n ")" ::: "memory")
; #define PG8_WAIT_L(n) asm volatile("s_waitcnt lgkmcnt(" #n ")" ::: "memory")
; #define PG8_BAR __builtin_amdgcn_s_barrier()
; #define PG8_SCHED __builtin_amdgcn_sched_barrier(0)
; template <class Epi, class Sched, bool ALIGN_EPI = false, bool SP2 = false>
; __device__ __forceinline__ void gemm_phase(PG8_LAS unsigned char* lds, const Gemm g, const Sched& S, const Epi& E) {
;     ...
;             const bool last = (t == nt - 2);
;             const char* a1 = cA + (size_t)(t + 1) * kstep;
;             const char* a2 = last ? nA : cA + (size_t)(t + 2) * kstep; const char* b2 = last ? nB : cB + (size_t)(t + 2) * kstep;
;             const char* a3 = a2 + kstep; const char* b3 = b2 + kstep;
;             if (last && has_next) S.a_ready(nxt);
;             if constexpr (SP2) {
;             PG8_LDB(B0, 0, 0); PG8_LDB(B1, 0, 1); PG8_SCHED; PG8_LDA(At, 0, 0); PG8_STAGE(PG8_SA(1, 1), a1 + hstep, voffA);
;             PG8_WAIT_V(8); PG8_WAIT_L(0); PG8_BAR; PG8_MMA(0, 0, At, B0); PG8_MMA(0, 1, At, B1); PG8_BAR; PG8_SCHED;
;             if (full) PG8_LDA(At, 0, 1); PG8_STAGE(PG8_SB(0, 0), b2, voffB); PG8_STAGE(PG8_SB(0, 1), b2 + hstep, voffB); PG8_STAGE(PG8_SA(0, 0), a2, voffA);
.LBB0_292:
	v_add_u32_e32 v0, 0x10000, v223
	ds_read_b128 v[148:151], v0
	ds_read_b128 v[152:155], v0 offset:1024
	ds_read_b128 v[156:159], v0 offset:2048
	ds_read_b128 v[160:163], v0 offset:3072
	v_add_u32_e32 v0, 0x14000, v223
	ds_read_b128 v[132:135], v0
	ds_read_b128 v[136:139], v0 offset:1024
	ds_read_b128 v[140:143], v0 offset:2048
	ds_read_b128 v[144:147], v0 offset:3072
	v_lshl_add_u64 v[2:3], s[36:37], 0, v[204:205]
	s_add_i32 m0, s31, 0xc000
	ds_read_b128 v[176:179], v224
	ds_read_b128 v[192:195], v224 offset:1024
	ds_read_b128 v[172:175], v224 offset:2048
	ds_read_b128 v[188:191], v224 offset:3072
	ds_read_b128 v[168:171], v224 offset:4096
	ds_read_b128 v[184:187], v224 offset:5120
	ds_read_b128 v[164:167], v224 offset:6144
	ds_read_b128 v[180:183], v224 offset:7168
	global_load_lds_dwordx4 v[2:3], off
	v_lshl_add_u64 v[2:3], s[36:37], 0, v[206:207]
	s_add_i32 m0, s31, 0xe000
	s_nop 0
	global_load_lds_dwordx4 v[2:3], off
	s_waitcnt vmcnt(8)
	s_waitcnt lgkmcnt(0)
	s_setprio 1
	s_barrier
	s_waitcnt lgkmcnt(0)
	v_mfma_f32_16x16x32_bf16 v[128:131], v[148:151], v[176:179], v[128:131]
	v_mfma_f32_16x16x32_bf16 v[124:127], v[156:159], v[176:179], v[124:127]
	v_mfma_f32_16x16x32_bf16 v[112:115], v[148:151], v[172:175], v[112:115]
	v_mfma_f32_16x16x32_bf16 v[108:111], v[156:159], v[172:175], v[108:111]
	v_mfma_f32_16x16x32_bf16 v[96:99], v[148:151], v[168:171], v[96:99]
	v_mfma_f32_16x16x32_bf16 v[92:95], v[156:159], v[168:171], v[92:95]
	v_mfma_f32_16x16x32_bf16 v[80:83], v[148:151], v[164:167], v[80:83]
	v_mfma_f32_16x16x32_bf16 v[76:79], v[156:159], v[164:167], v[76:79]
	v_mfma_f32_16x16x32_bf16 v[128:131], v[152:155], v[192:195], v[128:131]
	v_mfma_f32_16x16x32_bf16 v[124:127], v[160:163], v[192:195], v[124:127]
	v_mfma_f32_16x16x32_bf16 v[112:115], v[152:155], v[188:191], v[112:115]
	v_mfma_f32_16x16x32_bf16 v[108:111], v[160:163], v[188:191], v[108:111]
	v_mfma_f32_16x16x32_bf16 v[96:99], v[152:155], v[184:187], v[96:99]
	v_mfma_f32_16x16x32_bf16 v[92:95], v[160:163], v[184:187], v[92:95]
	v_mfma_f32_16x16x32_bf16 v[80:83], v[152:155], v[180:183], v[80:83]
	v_mfma_f32_16x16x32_bf16 v[76:79], v[160:163], v[180:183], v[76:79]
	s_setprio 0
	s_setprio 1
	v_mfma_f32_16x16x32_bf16 v[120:123], v[132:135], v[176:179], v[120:123]
	v_mfma_f32_16x16x32_bf16 v[116:119], v[140:143], v[176:179], v[116:119]
	v_mfma_f32_16x16x32_bf16 v[104:107], v[132:135], v[172:175], v[104:107]
	v_mfma_f32_16x16x32_bf16 v[100:103], v[140:143], v[172:175], v[100:103]
	v_mfma_f32_16x16x32_bf16 v[88:91], v[132:135], v[168:171], v[88:91]
	v_mfma_f32_16x16x32_bf16 v[84:87], v[140:143], v[168:171], v[84:87]
	v_mfma_f32_16x16x32_bf16 v[72:75], v[132:135], v[164:167], v[72:75]
	v_mfma_f32_16x16x32_bf16 v[68:71], v[140:143], v[164:167], v[68:71]
	v_mfma_f32_16x16x32_bf16 v[120:123], v[136:139], v[192:195], v[120:123]
	v_mfma_f32_16x16x32_bf16 v[116:119], v[144:147], v[192:195], v[116:119]
	v_mfma_f32_16x16x32_bf16 v[104:107], v[136:139], v[188:191], v[104:107]
	v_mfma_f32_16x16x32_bf16 v[100:103], v[144:147], v[188:191], v[100:103]
	v_mfma_f32_16x16x32_bf16 v[88:91], v[136:139], v[184:187], v[88:91]
	v_mfma_f32_16x16x32_bf16 v[84:87], v[144:147], v[184:187], v[84:87]
	v_mfma_f32_16x16x32_bf16 v[72:75], v[136:139], v[180:183], v[72:75]
	v_mfma_f32_16x16x32_bf16 v[68:71], v[144:147], v[180:183], v[68:71]
	s_barrier
	s_setprio 0
	v_cndmask_b32_e64 v0, 0, 1, s[34:35]
	v_cmp_ne_u32_e64 s[4:5], 1, v0
	s_andn2_b64 vcc, exec, s[34:35]
	s_cbranch_vccnz .LBB0_294
	ds_read_b128 v[176:179], v224 offset:16384
	ds_read_b128 v[192:195], v224 offset:17408
	ds_read_b128 v[172:175], v224 offset:18432
	ds_read_b128 v[188:191], v224 offset:19456
	ds_read_b128 v[168:171], v224 offset:20480
	ds_read_b128 v[184:187], v224 offset:21504
	ds_read_b128 v[164:167], v224 offset:22528
	ds_read_b128 v[180:183], v224 offset:23552
.LBB0_294:
	s_add_u32 s38, s36, 0xfffc0080
	s_addc_u32 s39, s37, -1
	s_cmp_eq_u32 s89, 12
	s_cselect_b32 s43, s23, s39
	s_cselect_b32 s42, s81, s38
	s_cselect_b32 s39, s21, s88
	s_cselect_b32 s38, s82, s83
	s_mov_b32 m0, s54
	v_lshl_add_u64 v[2:3], s[38:39], 0, v[198:199]
	s_add_u32 s90, s38, 0x40000
	global_load_lds_dwordx4 v[2:3], off
	v_lshl_add_u64 v[208:209], s[38:39], 0, v[202:203]
	s_mov_b32 m0, s55
	s_addc_u32 s91, s39, 0
	global_load_lds_dwordx4 v[208:209], off
	v_lshl_add_u64 v[210:211], s[90:91], 0, v[198:199]
	s_mov_b32 m0, s56
	v_lshl_add_u64 v[220:221], s[42:43], 0, v[200:201]
	global_load_lds_dwordx4 v[210:211], off
	v_lshl_add_u64 v[210:211], s[90:91], 0, v[202:203]
	s_mov_b32 m0, s57
	s_and_b64 vcc, exec, s[4:5]
	global_load_lds_dwordx4 v[210:211], off
	v_lshl_add_u64 v[210:211], s[42:43], 0, v[196:197]
	s_mov_b32 m0, s31
	s_nop 0
	global_load_lds_dwordx4 v[210:211], off
	s_mov_b32 m0, s58
	s_nop 0
	global_load_lds_dwordx4 v[220:221], off
	s_waitcnt vmcnt(8)
	s_waitcnt lgkmcnt(0)
	s_setprio 1
	s_barrier
	s_cbranch_vccnz .LBB0_296
; #define PG8_STAGE(bufoff, gbase, voff) do { _Pragma("unroll") for (int _i = 0; _i < 2; ++_i) \
;         __builtin_amdgcn_global_load_lds((const unsigned*)((const char*)(gbase) + (voff)[_i]), (PG8_LAS unsigned*)(lds + (bufoff) + ldsw + _i * 8192), 16, 0, 0); } while (0)
; #define PG8_LDA(dst, b, h) do { _Pragma("unroll") for (int m = 0; m < 4; ++m) _Pragma("unroll") for (int k = 0; k < 2; ++k) dst[m][k] = *(const PG8_LAS bf16x8*)(lds + PG8_SA(b, h) + aoff + m * 2048 + k * 1024); } while (0)
; #define PG8_LDB(dst, b, h) do { _Pragma("unroll") for (int n = 0; n < 2; ++n) _Pragma("unroll") for (int k = 0; k < 2; ++k) dst[n][k] = *(const PG8_LAS bf16x8*)(lds + PG8_SB(b, h) + boff + n * 2048 + k * 1024); } while (0)
; #define PG8_MMA(ai, bj, At, Bt) do { __builtin_amdgcn_s_setprio(1); _Pragma("unroll") for (int m = 0; m < 4; ++m) _Pragma("unroll") for (int n = 0; n < 2; ++n) _Pragma("unroll") for (int k = 0; k < 2; ++k) \
;         acc[ai][bj][m][n] = __builtin_amdgcn_mfma_f32_16x16x32_bf16(Bt[n][k], At[m][k], acc[ai][bj][m][n], 0, 0, 0); __builtin_amdgcn_s_setprio(0); } while (0)
; #define PG8_WAIT_V(n) asm volatile("s_waitcnt vmcnt(" #n ")" ::: "memory")
; #define PG8_WAIT_L(n) asm volatile("s_waitcnt lgkmcnt(" #n ")" ::: "memory")
; #define PG8_BAR __builtin_amdgcn_s_barrier()
; #define PG8_SCHED __builtin_amdgcn_sched_barrier(0)
; template <class Epi, class Sched, bool ALIGN_EPI = false, bool SP2 = false>
; __device__ __forceinline__ void gemm_phase(PG8_LAS unsigned char* lds, const Gemm g, const Sched& S, const Epi& E) {
;     ...
;             PG8_WAIT_V(8); PG8_WAIT_L(0); PG8_BAR; if (full) { PG8_MMA(1, 0, At, B0); PG8_MMA(1, 1, At, B1); } PG8_BAR; PG8_SCHED;
;             PG8_LDB(B0, 1, 0); PG8_LDB(B1, 1, 1); PG8_SCHED; PG8_LDA(At, 1, 0); PG8_STAGE(PG8_SA(0, 1), a2 + hstep, voffA);
;             PG8_WAIT_V(8); PG8_WAIT_L(0); PG8_BAR; PG8_MMA(0, 0, At, B0); PG8_MMA(0, 1, At, B1); PG8_BAR; PG8_SCHED;
	s_setprio 1
	s_waitcnt lgkmcnt(0)
	v_mfma_f32_16x16x32_bf16 v[64:67], v[148:151], v[176:179], v[64:67]
	v_mfma_f32_16x16x32_bf16 v[56:59], v[156:159], v[176:179], v[56:59]
	v_mfma_f32_16x16x32_bf16 v[48:51], v[148:151], v[172:175], v[48:51]
	v_mfma_f32_16x16x32_bf16 v[40:43], v[156:159], v[172:175], v[40:43]
	v_mfma_f32_16x16x32_bf16 v[32:35], v[148:151], v[168:171], v[32:35]
	v_mfma_f32_16x16x32_bf16 v[24:27], v[156:159], v[168:171], v[24:27]
	v_mfma_f32_16x16x32_bf16 v[16:19], v[148:151], v[164:167], v[16:19]
	v_mfma_f32_16x16x32_bf16 v[8:11], v[156:159], v[164:167], v[8:11]
	v_mfma_f32_16x16x32_bf16 v[64:67], v[152:155], v[192:195], v[64:67]
	v_mfma_f32_16x16x32_bf16 v[56:59], v[160:163], v[192:195], v[56:59]
	v_mfma_f32_16x16x32_bf16 v[48:51], v[152:155], v[188:191], v[48:51]
	v_mfma_f32_16x16x32_bf16 v[40:43], v[160:163], v[188:191], v[40:43]
	v_mfma_f32_16x16x32_bf16 v[32:35], v[152:155], v[184:187], v[32:35]
	v_mfma_f32_16x16x32_bf16 v[24:27], v[160:163], v[184:187], v[24:27]
	v_mfma_f32_16x16x32_bf16 v[16:19], v[152:155], v[180:183], v[16:19]
	v_mfma_f32_16x16x32_bf16 v[8:11], v[160:163], v[180:183], v[8:11]
	s_setprio 0
	s_setprio 1
	v_mfma_f32_16x16x32_bf16 v[60:63], v[132:135], v[176:179], v[60:63]
	v_mfma_f32_16x16x32_bf16 v[52:55], v[140:143], v[176:179], v[52:55]
	v_mfma_f32_16x16x32_bf16 v[44:47], v[132:135], v[172:175], v[44:47]
	v_mfma_f32_16x16x32_bf16 v[36:39], v[140:143], v[172:175], v[36:39]
	v_mfma_f32_16x16x32_bf16 v[28:31], v[132:135], v[168:171], v[28:31]
	v_mfma_f32_16x16x32_bf16 v[20:23], v[140:143], v[168:171], v[20:23]
	v_mfma_f32_16x16x32_bf16 v[12:15], v[132:135], v[164:167], v[12:15]
	v_mfma_f32_16x16x32_bf16 v[4:7], v[140:143], v[164:167], v[4:7]
	v_mfma_f32_16x16x32_bf16 v[60:63], v[136:139], v[192:195], v[60:63]
	v_mfma_f32_16x16x32_bf16 v[52:55], v[144:147], v[192:195], v[52:55]
	v_mfma_f32_16x16x32_bf16 v[44:47], v[136:139], v[188:191], v[44:47]
	v_mfma_f32_16x16x32_bf16 v[36:39], v[144:147], v[188:191], v[36:39]
	v_mfma_f32_16x16x32_bf16 v[28:31], v[136:139], v[184:187], v[28:31]
	v_mfma_f32_16x16x32_bf16 v[20:23], v[144:147], v[184:187], v[20:23]
	v_mfma_f32_16x16x32_bf16 v[12:15], v[136:139], v[180:183], v[12:15]
	v_mfma_f32_16x16x32_bf16 v[4:7], v[144:147], v[180:183], v[4:7]
.LBB0_296:
	s_barrier
	s_setprio 0
	v_add_u32_e32 v0, 0x18000, v223
	ds_read_b128 v[148:151], v0
	ds_read_b128 v[152:155], v0 offset:1024
	ds_read_b128 v[156:159], v0 offset:2048
	ds_read_b128 v[160:163], v0 offset:3072
	v_add_u32_e32 v0, 0x1c000, v223
	ds_read_b128 v[132:135], v0
	ds_read_b128 v[136:139], v0 offset:1024
	ds_read_b128 v[140:143], v0 offset:2048
	ds_read_b128 v[144:147], v0 offset:3072
	s_add_u32 s42, s42, 0x40000
	s_addc_u32 s43, s43, 0
	s_mov_b32 m0, s59
	v_lshl_add_u64 v[212:213], s[42:43], 0, v[196:197]
	ds_read_b128 v[176:179], v224 offset:32768
	ds_read_b128 v[192:195], v224 offset:33792
	ds_read_b128 v[172:175], v224 offset:34816
	ds_read_b128 v[188:191], v224 offset:35840
	ds_read_b128 v[168:171], v224 offset:36864
	ds_read_b128 v[184:187], v224 offset:37888
	ds_read_b128 v[164:167], v224 offset:38912
	ds_read_b128 v[180:183], v224 offset:39936
	global_load_lds_dwordx4 v[212:213], off
	v_lshl_add_u64 v[212:213], s[42:43], 0, v[200:201]
	s_mov_b32 m0, s60
	s_nop 0
	global_load_lds_dwordx4 v[212:213], off
	s_waitcnt vmcnt(8)
	s_waitcnt lgkmcnt(0)
	s_setprio 1
	s_barrier
	s_waitcnt lgkmcnt(0)
	v_mfma_f32_16x16x32_bf16 v[128:131], v[148:151], v[176:179], v[128:131]
	v_mfma_f32_16x16x32_bf16 v[124:127], v[156:159], v[176:179], v[124:127]
	v_mfma_f32_16x16x32_bf16 v[112:115], v[148:151], v[172:175], v[112:115]
	v_mfma_f32_16x16x32_bf16 v[108:111], v[156:159], v[172:175], v[108:111]
	v_mfma_f32_16x16x32_bf16 v[96:99], v[148:151], v[168:171], v[96:99]
	v_mfma_f32_16x16x32_bf16 v[92:95], v[156:159], v[168:171], v[92:95]
	v_mfma_f32_16x16x32_bf16 v[80:83], v[148:151], v[164:167], v[80:83]
	v_mfma_f32_16x16x32_bf16 v[76:79], v[156:159], v[164:167], v[76:79]
	v_mfma_f32_16x16x32_bf16 v[128:131], v[152:155], v[192:195], v[128:131]
	v_mfma_f32_16x16x32_bf16 v[124:127], v[160:163], v[192:195], v[124:127]
	v_mfma_f32_16x16x32_bf16 v[112:115], v[152:155], v[188:191], v[112:115]
	v_mfma_f32_16x16x32_bf16 v[108:111], v[160:163], v[188:191], v[108:111]
	v_mfma_f32_16x16x32_bf16 v[96:99], v[152:155], v[184:187], v[96:99]
	v_mfma_f32_16x16x32_bf16 v[92:95], v[160:163], v[184:187], v[92:95]
	v_mfma_f32_16x16x32_bf16 v[80:83], v[152:155], v[180:183], v[80:83]
	v_mfma_f32_16x16x32_bf16 v[76:79], v[160:163], v[180:183], v[76:79]
	s_setprio 0
	s_setprio 1
	v_mfma_f32_16x16x32_bf16 v[120:123], v[132:135], v[176:179], v[120:123]
	v_mfma_f32_16x16x32_bf16 v[116:119], v[140:143], v[176:179], v[116:119]
	v_mfma_f32_16x16x32_bf16 v[104:107], v[132:135], v[172:175], v[104:107]
	v_mfma_f32_16x16x32_bf16 v[100:103], v[140:143], v[172:175], v[100:103]
	v_mfma_f32_16x16x32_bf16 v[88:91], v[132:135], v[168:171], v[88:91]
	v_mfma_f32_16x16x32_bf16 v[84:87], v[140:143], v[168:171], v[84:87]
	v_mfma_f32_16x16x32_bf16 v[72:75], v[132:135], v[164:167], v[72:75]
	v_mfma_f32_16x16x32_bf16 v[68:71], v[140:143], v[164:167], v[68:71]
	v_mfma_f32_16x16x32_bf16 v[120:123], v[136:139], v[192:195], v[120:123]
	v_mfma_f32_16x16x32_bf16 v[116:119], v[144:147], v[192:195], v[116:119]
	v_mfma_f32_16x16x32_bf16 v[104:107], v[136:139], v[188:191], v[104:107]
	v_mfma_f32_16x16x32_bf16 v[100:103], v[144:147], v[188:191], v[100:103]
	v_mfma_f32_16x16x32_bf16 v[88:91], v[136:139], v[184:187], v[88:91]
	v_mfma_f32_16x16x32_bf16 v[84:87], v[144:147], v[184:187], v[84:87]
	v_mfma_f32_16x16x32_bf16 v[72:75], v[136:139], v[180:183], v[72:75]
	v_mfma_f32_16x16x32_bf16 v[68:71], v[144:147], v[180:183], v[68:71]
	s_barrier
	s_setprio 0
	s_and_b64 vcc, exec, s[4:5]
	s_cbranch_vccnz .LBB0_298
	ds_read_b128 v[176:179], v224 offset:49152
	ds_read_b128 v[192:195], v224 offset:50176
	ds_read_b128 v[172:175], v224 offset:51200
	ds_read_b128 v[188:191], v224 offset:52224
	ds_read_b128 v[168:171], v224 offset:53248
	ds_read_b128 v[184:187], v224 offset:54272
	ds_read_b128 v[164:167], v224 offset:55296
	ds_read_b128 v[180:183], v224 offset:56320
; #define PG8_STAGE(bufoff, gbase, voff) do { _Pragma("unroll") for (int _i = 0; _i < 2; ++_i) \
;         __builtin_amdgcn_global_load_lds((const unsigned*)((const char*)(gbase) + (voff)[_i]), (PG8_LAS unsigned*)(lds + (bufoff) + ldsw + _i * 8192), 16, 0, 0); } while (0)
; #define PG8_LDA(dst, b, h) do { _Pragma("unroll") for (int m = 0; m < 4; ++m) _Pragma("unroll") for (int k = 0; k < 2; ++k) dst[m][k] = *(const PG8_LAS bf16x8*)(lds + PG8_SA(b, h) + aoff + m * 2048 + k * 1024); } while (0)
; #define PG8_MMA(ai, bj, At, Bt) do { __builtin_amdgcn_s_setprio(1); _Pragma("unroll") for (int m = 0; m < 4; ++m) _Pragma("unroll") for (int n = 0; n < 2; ++n) _Pragma("unroll") for (int k = 0; k < 2; ++k) \
;         acc[ai][bj][m][n] = __builtin_amdgcn_mfma_f32_16x16x32_bf16(Bt[n][k], At[m][k], acc[ai][bj][m][n], 0, 0, 0); __builtin_amdgcn_s_setprio(0); } while (0)
; #define PG8_WAIT_V(n) asm volatile("s_waitcnt vmcnt(" #n ")" ::: "memory")
; #define PG8_WAIT_L(n) asm volatile("s_waitcnt lgkmcnt(" #n ")" ::: "memory")
; #define PG8_BAR __builtin_amdgcn_s_barrier()
; #define PG8_SCHED __builtin_amdgcn_sched_barrier(0)
; template <class Epi, class Sched, bool ALIGN_EPI = false, bool SP2 = false>
; __device__ __forceinline__ void gemm_phase(PG8_LAS unsigned char* lds, const Gemm g, const Sched& S, const Epi& E) {
;     ...
;             if (full) PG8_LDA(At, 1, 1); PG8_STAGE(PG8_SB(1, 0), b3, voffB); PG8_STAGE(PG8_SB(1, 1), b3 + hstep, voffB); PG8_STAGE(PG8_SA(1, 0), a3, voffA);
;             PG8_WAIT_V(8); PG8_WAIT_L(0); PG8_BAR; if (full) { PG8_MMA(1, 0, At, B0); PG8_MMA(1, 1, At, B1); } PG8_BAR; PG8_SCHED;
.LBB0_298:
	s_mov_b32 m0, s61
	v_lshl_add_u64 v[2:3], v[2:3], 0, s[52:53]
	s_add_u32 s38, s38, 0x40080
	global_load_lds_dwordx4 v[2:3], off
	v_lshl_add_u64 v[2:3], v[208:209], 0, s[52:53]
	s_mov_b32 m0, s62
	s_addc_u32 s39, s39, 0
	global_load_lds_dwordx4 v[2:3], off
	v_lshl_add_u64 v[2:3], s[38:39], 0, v[198:199]
	s_mov_b32 m0, s65
	s_and_b64 vcc, exec, s[4:5]
	global_load_lds_dwordx4 v[2:3], off
	v_lshl_add_u64 v[2:3], s[38:39], 0, v[202:203]
	s_mov_b32 m0, s68
	s_nop 0
	global_load_lds_dwordx4 v[2:3], off
	v_lshl_add_u64 v[2:3], v[210:211], 0, s[52:53]
	s_mov_b32 m0, s63
	s_nop 0
	global_load_lds_dwordx4 v[2:3], off
	v_lshl_add_u64 v[2:3], v[220:221], 0, s[52:53]
	s_mov_b32 m0, s64
	s_nop 0
	global_load_lds_dwordx4 v[2:3], off
	s_waitcnt vmcnt(8)
	s_waitcnt lgkmcnt(0)
	s_setprio 1
	s_barrier
	s_cbranch_vccnz .LBB0_291
	s_setprio 1
	s_waitcnt lgkmcnt(0)
	v_mfma_f32_16x16x32_bf16 v[64:67], v[148:151], v[176:179], v[64:67]
	v_mfma_f32_16x16x32_bf16 v[56:59], v[156:159], v[176:179], v[56:59]
	v_mfma_f32_16x16x32_bf16 v[48:51], v[148:151], v[172:175], v[48:51]
	v_mfma_f32_16x16x32_bf16 v[40:43], v[156:159], v[172:175], v[40:43]
	v_mfma_f32_16x16x32_bf16 v[32:35], v[148:151], v[168:171], v[32:35]
	v_mfma_f32_16x16x32_bf16 v[24:27], v[156:159], v[168:171], v[24:27]
	v_mfma_f32_16x16x32_bf16 v[16:19], v[148:151], v[164:167], v[16:19]
	v_mfma_f32_16x16x32_bf16 v[8:11], v[156:159], v[164:167], v[8:11]
	v_mfma_f32_16x16x32_bf16 v[64:67], v[152:155], v[192:195], v[64:67]
	v_mfma_f32_16x16x32_bf16 v[56:59], v[160:163], v[192:195], v[56:59]
	v_mfma_f32_16x16x32_bf16 v[48:51], v[152:155], v[188:191], v[48:51]
	v_mfma_f32_16x16x32_bf16 v[40:43], v[160:163], v[188:191], v[40:43]
	v_mfma_f32_16x16x32_bf16 v[32:35], v[152:155], v[184:187], v[32:35]
	v_mfma_f32_16x16x32_bf16 v[24:27], v[160:163], v[184:187], v[24:27]
	v_mfma_f32_16x16x32_bf16 v[16:19], v[152:155], v[180:183], v[16:19]
	v_mfma_f32_16x16x32_bf16 v[8:11], v[160:163], v[180:183], v[8:11]
	s_setprio 0
	s_setprio 1
	v_mfma_f32_16x16x32_bf16 v[60:63], v[132:135], v[176:179], v[60:63]
	v_mfma_f32_16x16x32_bf16 v[52:55], v[140:143], v[176:179], v[52:55]
	v_mfma_f32_16x16x32_bf16 v[44:47], v[132:135], v[172:175], v[44:47]
	v_mfma_f32_16x16x32_bf16 v[36:39], v[140:143], v[172:175], v[36:39]
	v_mfma_f32_16x16x32_bf16 v[28:31], v[132:135], v[168:171], v[28:31]
	v_mfma_f32_16x16x32_bf16 v[20:23], v[140:143], v[168:171], v[20:23]
	v_mfma_f32_16x16x32_bf16 v[12:15], v[132:135], v[164:167], v[12:15]
	v_mfma_f32_16x16x32_bf16 v[2:5], v[140:143], v[164:167], v[4:7]
	v_mfma_f32_16x16x32_bf16 v[60:63], v[136:139], v[192:195], v[60:63]
	v_mfma_f32_16x16x32_bf16 v[52:55], v[144:147], v[192:195], v[52:55]
	v_mfma_f32_16x16x32_bf16 v[44:47], v[136:139], v[188:191], v[44:47]
	v_mfma_f32_16x16x32_bf16 v[36:39], v[144:147], v[188:191], v[36:39]
	v_mfma_f32_16x16x32_bf16 v[28:31], v[136:139], v[184:187], v[28:31]
	v_mfma_f32_16x16x32_bf16 v[20:23], v[144:147], v[184:187], v[20:23]
	v_mfma_f32_16x16x32_bf16 v[12:15], v[136:139], v[180:183], v[12:15]
	v_mfma_f32_16x16x32_bf16 v[4:7], v[144:147], v[180:183], v[2:5]
	s_branch .LBB0_291

; #define PG8_STAGE(bufoff, gbase, voff) do { _Pragma("unroll") for (int _i = 0; _i < 2; ++_i) \
;         __builtin_amdgcn_global_load_lds((const unsigned*)((const char*)(gbase) + (voff)[_i]), (PG8_LAS unsigned*)(lds + (bufoff) + ldsw + _i * 8192), 16, 0, 0); } while (0)
; #define PG8_LDA(dst, b, h) do { _Pragma("unroll") for (int m = 0; m < 4; ++m) _Pragma("unroll") for (int k = 0; k < 2; ++k) dst[m][k] = *(const PG8_LAS bf16x8*)(lds + PG8_SA(b, h) + aoff + m * 2048 + k * 1024); } while (0)
; #define PG8_LDB(dst, b, h) do { _Pragma("unroll") for (int n = 0; n < 2; ++n) _Pragma("unroll") for (int k = 0; k < 2; ++k) dst[n][k] = *(const PG8_LAS bf16x8*)(lds + PG8_SB(b, h) + boff + n * 2048 + k * 1024); } while (0)
; #define PG8_MMA(ai, bj, At, Bt) do { __builtin_amdgcn_s_setprio(1); _Pragma("unroll") for (int m = 0; m < 4; ++m) _Pragma("unroll") for (int n = 0; n < 2; ++n) _Pragma("unroll") for (int k = 0; k < 2; ++k) \
;         acc[ai][bj][m][n] = __builtin_amdgcn_mfma_f32_16x16x32_bf16(Bt[n][k], At[m][k], acc[ai][bj][m][n], 0, 0, 0); __builtin_amdgcn_s_setprio(0); } while (0)
; #define PG8_WAIT_V(n) asm volatile("s_waitcnt vmcnt(" #n ")" ::: "memory")
; #define PG8_WAIT_L(n) asm volatile("s_waitcnt lgkmcnt(" #n ")" ::: "memory")
; #define PG8_BAR __builtin_amdgcn_s_barrier()
; #define PG8_SCHED __builtin_amdgcn_sched_barrier(0)
; template <class Epi, class Sched, bool ALIGN_EPI = false, bool SP2 = false>
; __device__ __forceinline__ void gemm_phase(PG8_LAS unsigned char* lds, const Gemm g, const Sched& S, const Epi& E) {
;     ...
;             const bool last = (t == nt - 2);
;             const char* a1 = cA + (size_t)(t + 1) * kstep;
;             const char* a2 = last ? nA : cA + (size_t)(t + 2) * kstep; const char* b2 = last ? nB : cB + (size_t)(t + 2) * kstep;
;             const char* a3 = a2 + kstep; const char* b3 = b2 + kstep;
;             if (last && has_next) S.a_ready(nxt);
;             if constexpr (SP2) {
;             PG8_LDB(B0, 0, 0); PG8_LDB(B1, 0, 1); PG8_SCHED; PG8_LDA(At, 0, 0); PG8_STAGE(PG8_SA(1, 1), a1 + hstep, voffA);
;             PG8_WAIT_V(8); PG8_WAIT_L(0); PG8_BAR; PG8_MMA(0, 0, At, B0); PG8_MMA(0, 1, At, B1); PG8_BAR; PG8_SCHED;
;             if (full) PG8_LDA(At, 0, 1); PG8_STAGE(PG8_SB(0, 0), b2, voffB); PG8_STAGE(PG8_SB(0, 1), b2 + hstep, voffB); PG8_STAGE(PG8_SA(0, 0), a2, voffA);
.LBB0_382:
	s_add_u32 s30, s24, s28
	s_addc_u32 s31, s25, s29
	s_add_u32 s30, s30, 0x100
	s_addc_u32 s31, s31, 0
	s_add_u32 s65, s62, s28
	s_addc_u32 s68, s63, s29
	s_add_i32 s69, 0, 0x10000
	s_cmpk_eq_i32 s28, 0x1500
	s_cselect_b32 s35, s27, s31
	s_cselect_b32 s34, s26, s30
	v_add_u32_e32 v146, s69, v140
	s_cselect_b32 s31, s9, s68
	s_cselect_b32 s30, s8, s65
	s_add_i32 s65, 0, 0x14000
	ds_read_b128 v[142:145], v146
	ds_read_b128 v[154:157], v146 offset:1024
	ds_read_b128 v[158:161], v146 offset:2048
	ds_read_b128 v[162:165], v146 offset:3072
	v_add_u32_e32 v146, s65, v140
	ds_read_b128 v[166:169], v146
	ds_read_b128 v[170:173], v146 offset:1024
	ds_read_b128 v[174:177], v146 offset:2048
	ds_read_b128 v[178:181], v146 offset:3072
	v_lshl_add_u64 v[146:147], v[136:137], 0, s[28:29]
	s_add_i32 m0, s44, 0xc000
	ds_read_b128 v[182:185], v141
	ds_read_b128 v[186:189], v141 offset:1024
	ds_read_b128 v[190:193], v141 offset:2048
	ds_read_b128 v[194:197], v141 offset:3072
	ds_read_b128 v[198:201], v141 offset:4096
	ds_read_b128 v[202:205], v141 offset:5120
	ds_read_b128 v[206:209], v141 offset:6144
	ds_read_b128 v[220:223], v141 offset:7168
	global_load_lds_dwordx4 v[146:147], off
	v_lshl_add_u64 v[146:147], v[138:139], 0, s[28:29]
	s_add_i32 m0, s44, 0xe000
	s_nop 0
	global_load_lds_dwordx4 v[146:147], off
	s_waitcnt vmcnt(8)
	s_waitcnt lgkmcnt(0)
	s_setprio 1
	s_barrier
	s_waitcnt lgkmcnt(0)
	v_mfma_f32_16x16x32_bf16 v[114:117], v[142:145], v[182:185], v[114:117]
	v_mfma_f32_16x16x32_bf16 v[82:85], v[158:161], v[182:185], v[82:85]
	v_mfma_f32_16x16x32_bf16 v[122:125], v[142:145], v[190:193], v[122:125]
	v_mfma_f32_16x16x32_bf16 v[94:97], v[158:161], v[190:193], v[94:97]
	v_mfma_f32_16x16x32_bf16 v[126:129], v[142:145], v[198:201], v[126:129]
	v_mfma_f32_16x16x32_bf16 v[106:109], v[158:161], v[198:201], v[106:109]
	v_mfma_f32_16x16x32_bf16 v[118:121], v[142:145], v[206:209], v[118:121]
	v_mfma_f32_16x16x32_bf16 v[110:113], v[158:161], v[206:209], v[110:113]
	v_mfma_f32_16x16x32_bf16 v[114:117], v[154:157], v[186:189], v[114:117]
	v_mfma_f32_16x16x32_bf16 v[82:85], v[162:165], v[186:189], v[82:85]
	v_mfma_f32_16x16x32_bf16 v[122:125], v[154:157], v[194:197], v[122:125]
	v_mfma_f32_16x16x32_bf16 v[94:97], v[162:165], v[194:197], v[94:97]
	v_mfma_f32_16x16x32_bf16 v[126:129], v[154:157], v[202:205], v[126:129]
	v_mfma_f32_16x16x32_bf16 v[106:109], v[162:165], v[202:205], v[106:109]
	v_mfma_f32_16x16x32_bf16 v[118:121], v[154:157], v[220:223], v[118:121]
	v_mfma_f32_16x16x32_bf16 v[110:113], v[162:165], v[220:223], v[110:113]
	s_setprio 0
	s_setprio 1
	v_mfma_f32_16x16x32_bf16 v[26:29], v[166:169], v[182:185], v[26:29]
	v_mfma_f32_16x16x32_bf16 v[2:5], v[174:177], v[182:185], v[2:5]
	v_mfma_f32_16x16x32_bf16 v[34:37], v[166:169], v[190:193], v[34:37]
	v_mfma_f32_16x16x32_bf16 v[6:9], v[174:177], v[190:193], v[6:9]
	v_mfma_f32_16x16x32_bf16 v[42:45], v[166:169], v[198:201], v[42:45]
	v_mfma_f32_16x16x32_bf16 v[10:13], v[174:177], v[198:201], v[10:13]
	v_mfma_f32_16x16x32_bf16 v[46:49], v[166:169], v[206:209], v[46:49]
	v_mfma_f32_16x16x32_bf16 v[14:17], v[174:177], v[206:209], v[14:17]
	v_mfma_f32_16x16x32_bf16 v[26:29], v[170:173], v[186:189], v[26:29]
	v_mfma_f32_16x16x32_bf16 v[2:5], v[178:181], v[186:189], v[2:5]
	v_mfma_f32_16x16x32_bf16 v[34:37], v[170:173], v[194:197], v[34:37]
	v_mfma_f32_16x16x32_bf16 v[6:9], v[178:181], v[194:197], v[6:9]
	v_mfma_f32_16x16x32_bf16 v[42:45], v[170:173], v[202:205], v[42:45]
	v_mfma_f32_16x16x32_bf16 v[10:13], v[178:181], v[202:205], v[10:13]
	v_mfma_f32_16x16x32_bf16 v[46:49], v[170:173], v[220:223], v[46:49]
	v_mfma_f32_16x16x32_bf16 v[14:17], v[178:181], v[220:223], v[14:17]
	s_barrier
	s_setprio 0
	s_add_i32 s68, s69, s43
	v_lshl_add_u64 v[146:147], s[30:31], 0, v[0:1]
	s_mov_b32 m0, s68
	ds_read_b128 v[182:185], v141 offset:16384
	ds_read_b128 v[186:189], v141 offset:17408
	ds_read_b128 v[190:193], v141 offset:18432
	ds_read_b128 v[194:197], v141 offset:19456
	ds_read_b128 v[198:201], v141 offset:20480
	ds_read_b128 v[202:205], v141 offset:21504
	ds_read_b128 v[206:209], v141 offset:22528
	ds_read_b128 v[220:223], v141 offset:23552
	global_load_lds_dwordx4 v[146:147], off
	s_add_i32 m0, s68, 0x2000
	s_add_u32 s68, s30, 0xb0000
	v_lshl_add_u64 v[150:151], s[30:31], 0, v[130:131]
	s_addc_u32 s69, s31, 0
	s_add_i32 s65, s65, s43
	global_load_lds_dwordx4 v[150:151], off
	v_lshl_add_u64 v[210:211], s[68:69], 0, v[0:1]
	s_mov_b32 m0, s65
	v_lshl_add_u64 v[212:213], s[34:35], 0, v[130:131]
	global_load_lds_dwordx4 v[210:211], off
	v_lshl_add_u64 v[210:211], s[68:69], 0, v[130:131]
	s_add_i32 m0, s65, 0x2000
	s_nop 0
	global_load_lds_dwordx4 v[210:211], off
	v_lshl_add_u64 v[210:211], s[34:35], 0, v[0:1]
	s_mov_b32 m0, s44
	s_nop 0
	global_load_lds_dwordx4 v[210:211], off
	s_mov_b32 m0, s45
	s_nop 0
	global_load_lds_dwordx4 v[212:213], off
	s_waitcnt vmcnt(8)
	s_waitcnt lgkmcnt(0)
	s_setprio 1
	s_barrier
; #define PG8_STAGE(bufoff, gbase, voff) do { _Pragma("unroll") for (int _i = 0; _i < 2; ++_i) \
;         __builtin_amdgcn_global_load_lds((const unsigned*)((const char*)(gbase) + (voff)[_i]), (PG8_LAS unsigned*)(lds + (bufoff) + ldsw + _i * 8192), 16, 0, 0); } while (0)
; #define PG8_LDA(dst, b, h) do { _Pragma("unroll") for (int m = 0; m < 4; ++m) _Pragma("unroll") for (int k = 0; k < 2; ++k) dst[m][k] = *(const PG8_LAS bf16x8*)(lds + PG8_SA(b, h) + aoff + m * 2048 + k * 1024); } while (0)
; #define PG8_LDB(dst, b, h) do { _Pragma("unroll") for (int n = 0; n < 2; ++n) _Pragma("unroll") for (int k = 0; k < 2; ++k) dst[n][k] = *(const PG8_LAS bf16x8*)(lds + PG8_SB(b, h) + boff + n * 2048 + k * 1024); } while (0)
; #define PG8_MMA(ai, bj, At, Bt) do { __builtin_amdgcn_s_setprio(1); _Pragma("unroll") for (int m = 0; m < 4; ++m) _Pragma("unroll") for (int n = 0; n < 2; ++n) _Pragma("unroll") for (int k = 0; k < 2; ++k) \
;         acc[ai][bj][m][n] = __builtin_amdgcn_mfma_f32_16x16x32_bf16(Bt[n][k], At[m][k], acc[ai][bj][m][n], 0, 0, 0); __builtin_amdgcn_s_setprio(0); } while (0)
; #define PG8_WAIT_V(n) asm volatile("s_waitcnt vmcnt(" #n ")" ::: "memory")
; #define PG8_WAIT_L(n) asm volatile("s_waitcnt lgkmcnt(" #n ")" ::: "memory")
; #define PG8_BAR __builtin_amdgcn_s_barrier()
; #define PG8_SCHED __builtin_amdgcn_sched_barrier(0)
; template <class Epi, class Sched, bool ALIGN_EPI = false, bool SP2 = false>
; __device__ __forceinline__ void gemm_phase(PG8_LAS unsigned char* lds, const Gemm g, const Sched& S, const Epi& E) {
;     ...
;             PG8_WAIT_V(8); PG8_WAIT_L(0); PG8_BAR; if (full) { PG8_MMA(1, 0, At, B0); PG8_MMA(1, 1, At, B1); } PG8_BAR; PG8_SCHED;
;             PG8_LDB(B0, 1, 0); PG8_LDB(B1, 1, 1); PG8_SCHED; PG8_LDA(At, 1, 0); PG8_STAGE(PG8_SA(0, 1), a2 + hstep, voffA);
;             PG8_WAIT_V(8); PG8_WAIT_L(0); PG8_BAR; PG8_MMA(0, 0, At, B0); PG8_MMA(0, 1, At, B1); PG8_BAR; PG8_SCHED;
	s_waitcnt lgkmcnt(0)
	v_mfma_f32_16x16x32_bf16 v[102:105], v[142:145], v[182:185], v[102:105]
	v_mfma_f32_16x16x32_bf16 v[98:101], v[158:161], v[182:185], v[98:101]
	v_mfma_f32_16x16x32_bf16 v[90:93], v[142:145], v[190:193], v[90:93]
	v_mfma_f32_16x16x32_bf16 v[86:89], v[158:161], v[190:193], v[86:89]
	v_mfma_f32_16x16x32_bf16 v[78:81], v[142:145], v[198:201], v[78:81]
	v_mfma_f32_16x16x32_bf16 v[74:77], v[158:161], v[198:201], v[74:77]
	v_mfma_f32_16x16x32_bf16 v[70:73], v[142:145], v[206:209], v[70:73]
	v_mfma_f32_16x16x32_bf16 v[66:69], v[158:161], v[206:209], v[66:69]
	v_mfma_f32_16x16x32_bf16 v[102:105], v[154:157], v[186:189], v[102:105]
	v_mfma_f32_16x16x32_bf16 v[98:101], v[162:165], v[186:189], v[98:101]
	v_mfma_f32_16x16x32_bf16 v[90:93], v[154:157], v[194:197], v[90:93]
	v_mfma_f32_16x16x32_bf16 v[86:89], v[162:165], v[194:197], v[86:89]
	v_mfma_f32_16x16x32_bf16 v[78:81], v[154:157], v[202:205], v[78:81]
	v_mfma_f32_16x16x32_bf16 v[74:77], v[162:165], v[202:205], v[74:77]
	v_mfma_f32_16x16x32_bf16 v[70:73], v[154:157], v[220:223], v[70:73]
	v_mfma_f32_16x16x32_bf16 v[66:69], v[162:165], v[220:223], v[66:69]
	s_setprio 0
	s_setprio 1
	v_mfma_f32_16x16x32_bf16 v[54:57], v[166:169], v[182:185], v[54:57]
	v_mfma_f32_16x16x32_bf16 v[18:21], v[174:177], v[182:185], v[18:21]
	v_mfma_f32_16x16x32_bf16 v[58:61], v[166:169], v[190:193], v[58:61]
	v_mfma_f32_16x16x32_bf16 v[30:33], v[174:177], v[190:193], v[30:33]
	v_mfma_f32_16x16x32_bf16 v[62:65], v[166:169], v[198:201], v[62:65]
	v_mfma_f32_16x16x32_bf16 v[38:41], v[174:177], v[198:201], v[38:41]
	v_mfma_f32_16x16x32_bf16 v[50:53], v[166:169], v[206:209], v[50:53]
	v_mfma_f32_16x16x32_bf16 v[22:25], v[174:177], v[206:209], v[22:25]
	v_mfma_f32_16x16x32_bf16 v[54:57], v[170:173], v[186:189], v[54:57]
	v_mfma_f32_16x16x32_bf16 v[18:21], v[178:181], v[186:189], v[18:21]
	v_mfma_f32_16x16x32_bf16 v[58:61], v[170:173], v[194:197], v[58:61]
	v_mfma_f32_16x16x32_bf16 v[30:33], v[178:181], v[194:197], v[30:33]
	v_mfma_f32_16x16x32_bf16 v[62:65], v[170:173], v[202:205], v[62:65]
	v_mfma_f32_16x16x32_bf16 v[38:41], v[178:181], v[202:205], v[38:41]
	v_mfma_f32_16x16x32_bf16 v[50:53], v[170:173], v[220:223], v[50:53]
	v_mfma_f32_16x16x32_bf16 v[22:25], v[178:181], v[220:223], v[22:25]
	s_barrier
	s_setprio 0
	s_add_i32 s65, 0, 0x18000
	v_add_u32_e32 v149, s65, v140
	s_add_i32 s68, 0, 0x1c000
	ds_read_b128 v[142:145], v149
	ds_read_b128 v[154:157], v149 offset:1024
	ds_read_b128 v[158:161], v149 offset:2048
	ds_read_b128 v[162:165], v149 offset:3072
	v_add_u32_e32 v149, s68, v140
	ds_read_b128 v[166:169], v149
	ds_read_b128 v[170:173], v149 offset:1024
	ds_read_b128 v[174:177], v149 offset:2048
	ds_read_b128 v[178:181], v149 offset:3072
	s_add_u32 s34, s34, 0xb0000
	s_addc_u32 s35, s35, 0
	s_mov_b32 m0, s48
	v_lshl_add_u64 v[214:215], s[34:35], 0, v[0:1]
	ds_read_b128 v[182:185], v141 offset:32768
	ds_read_b128 v[186:189], v141 offset:33792
	ds_read_b128 v[190:193], v141 offset:34816
	ds_read_b128 v[194:197], v141 offset:35840
	ds_read_b128 v[198:201], v141 offset:36864
	ds_read_b128 v[202:205], v141 offset:37888
	ds_read_b128 v[206:209], v141 offset:38912
	ds_read_b128 v[220:223], v141 offset:39936
	global_load_lds_dwordx4 v[214:215], off
	v_lshl_add_u64 v[214:215], s[34:35], 0, v[130:131]
	s_mov_b32 m0, s54
	s_nop 0
	global_load_lds_dwordx4 v[214:215], off
	s_waitcnt vmcnt(8)
	s_waitcnt lgkmcnt(0)
	s_setprio 1
	s_barrier
	s_waitcnt lgkmcnt(0)
	v_mfma_f32_16x16x32_bf16 v[114:117], v[142:145], v[182:185], v[114:117]
	v_mfma_f32_16x16x32_bf16 v[82:85], v[158:161], v[182:185], v[82:85]
	v_mfma_f32_16x16x32_bf16 v[122:125], v[142:145], v[190:193], v[122:125]
	v_mfma_f32_16x16x32_bf16 v[94:97], v[158:161], v[190:193], v[94:97]
	v_mfma_f32_16x16x32_bf16 v[126:129], v[142:145], v[198:201], v[126:129]
	v_mfma_f32_16x16x32_bf16 v[106:109], v[158:161], v[198:201], v[106:109]
	v_mfma_f32_16x16x32_bf16 v[118:121], v[142:145], v[206:209], v[118:121]
	v_mfma_f32_16x16x32_bf16 v[110:113], v[158:161], v[206:209], v[110:113]
	v_mfma_f32_16x16x32_bf16 v[114:117], v[154:157], v[186:189], v[114:117]
	v_mfma_f32_16x16x32_bf16 v[82:85], v[162:165], v[186:189], v[82:85]
	v_mfma_f32_16x16x32_bf16 v[122:125], v[154:157], v[194:197], v[122:125]
	v_mfma_f32_16x16x32_bf16 v[94:97], v[162:165], v[194:197], v[94:97]
	v_mfma_f32_16x16x32_bf16 v[126:129], v[154:157], v[202:205], v[126:129]
	v_mfma_f32_16x16x32_bf16 v[106:109], v[162:165], v[202:205], v[106:109]
	v_mfma_f32_16x16x32_bf16 v[118:121], v[154:157], v[220:223], v[118:121]
	v_mfma_f32_16x16x32_bf16 v[110:113], v[162:165], v[220:223], v[110:113]
	s_setprio 0
	s_setprio 1
	v_mfma_f32_16x16x32_bf16 v[26:29], v[166:169], v[182:185], v[26:29]
	v_mfma_f32_16x16x32_bf16 v[2:5], v[174:177], v[182:185], v[2:5]
	v_mfma_f32_16x16x32_bf16 v[34:37], v[166:169], v[190:193], v[34:37]
	v_mfma_f32_16x16x32_bf16 v[6:9], v[174:177], v[190:193], v[6:9]
	v_mfma_f32_16x16x32_bf16 v[42:45], v[166:169], v[198:201], v[42:45]
	v_mfma_f32_16x16x32_bf16 v[10:13], v[174:177], v[198:201], v[10:13]
	v_mfma_f32_16x16x32_bf16 v[46:49], v[166:169], v[206:209], v[46:49]
	v_mfma_f32_16x16x32_bf16 v[14:17], v[174:177], v[206:209], v[14:17]
	v_mfma_f32_16x16x32_bf16 v[26:29], v[170:173], v[186:189], v[26:29]
	v_mfma_f32_16x16x32_bf16 v[2:5], v[178:181], v[186:189], v[2:5]
	v_mfma_f32_16x16x32_bf16 v[34:37], v[170:173], v[194:197], v[34:37]
	v_mfma_f32_16x16x32_bf16 v[6:9], v[178:181], v[194:197], v[6:9]
	v_mfma_f32_16x16x32_bf16 v[42:45], v[170:173], v[202:205], v[42:45]
	v_mfma_f32_16x16x32_bf16 v[10:13], v[178:181], v[202:205], v[10:13]
	v_mfma_f32_16x16x32_bf16 v[46:49], v[170:173], v[220:223], v[46:49]
	v_mfma_f32_16x16x32_bf16 v[14:17], v[178:181], v[220:223], v[14:17]
	s_barrier
; #define PG8_STAGE(bufoff, gbase, voff) do { _Pragma("unroll") for (int _i = 0; _i < 2; ++_i) \
;         __builtin_amdgcn_global_load_lds((const unsigned*)((const char*)(gbase) + (voff)[_i]), (PG8_LAS unsigned*)(lds + (bufoff) + ldsw + _i * 8192), 16, 0, 0); } while (0)
; #define PG8_LDA(dst, b, h) do { _Pragma("unroll") for (int m = 0; m < 4; ++m) _Pragma("unroll") for (int k = 0; k < 2; ++k) dst[m][k] = *(const PG8_LAS bf16x8*)(lds + PG8_SA(b, h) + aoff + m * 2048 + k * 1024); } while (0)
; #define PG8_MMA(ai, bj, At, Bt) do { __builtin_amdgcn_s_setprio(1); _Pragma("unroll") for (int m = 0; m < 4; ++m) _Pragma("unroll") for (int n = 0; n < 2; ++n) _Pragma("unroll") for (int k = 0; k < 2; ++k) \
;         acc[ai][bj][m][n] = __builtin_amdgcn_mfma_f32_16x16x32_bf16(Bt[n][k], At[m][k], acc[ai][bj][m][n], 0, 0, 0); __builtin_amdgcn_s_setprio(0); } while (0)
; #define PG8_WAIT_V(n) asm volatile("s_waitcnt vmcnt(" #n ")" ::: "memory")
; #define PG8_WAIT_L(n) asm volatile("s_waitcnt lgkmcnt(" #n ")" ::: "memory")
; #define PG8_BAR __builtin_amdgcn_s_barrier()
; #define PG8_SCHED __builtin_amdgcn_sched_barrier(0)
; template <class Epi, class Sched, bool ALIGN_EPI = false, bool SP2 = false>
; __device__ __forceinline__ void gemm_phase(PG8_LAS unsigned char* lds, const Gemm g, const Sched& S, const Epi& E) {
;     ...
;             if (full) PG8_LDA(At, 1, 1); PG8_STAGE(PG8_SB(1, 0), b3, voffB); PG8_STAGE(PG8_SB(1, 1), b3 + hstep, voffB); PG8_STAGE(PG8_SA(1, 0), a3, voffA);
;             PG8_WAIT_V(8); PG8_WAIT_L(0); PG8_BAR; if (full) { PG8_MMA(1, 0, At, B0); PG8_MMA(1, 1, At, B1); } PG8_BAR; PG8_SCHED;
;     ...
;         if (!has_next) break;
;         if (!Sched::KEEP || (nxt.pn >> 2) == 0) {
; #pragma unroll
;         for (int a = 0; a < 2; ++a)
; #pragma unroll
;             for (int b = 0; b < 2; ++b)
; #pragma unroll
;                 for (int m = 0; m < 4; ++m)
; #pragma unroll
;                     for (int n = 0; n < 2; ++n) acc[a][b][m][n] = (f32x4){0.f, 0.f, 0.f, 0.f};
;         }
	s_setprio 0
	s_add_i32 s34, s65, s43
	v_lshl_add_u64 v[146:147], v[146:147], 0, s[52:53]
	s_mov_b32 m0, s34
	ds_read_b128 v[182:185], v141 offset:49152
	ds_read_b128 v[186:189], v141 offset:50176
	ds_read_b128 v[190:193], v141 offset:51200
	ds_read_b128 v[194:197], v141 offset:52224
	ds_read_b128 v[198:201], v141 offset:53248
	ds_read_b128 v[202:205], v141 offset:54272
	ds_read_b128 v[206:209], v141 offset:55296
	ds_read_b128 v[220:223], v141 offset:56320
	global_load_lds_dwordx4 v[146:147], off
	s_add_i32 m0, s34, 0x2000
	s_add_u32 s30, s30, 0xb0080
	v_lshl_add_u64 v[146:147], v[150:151], 0, s[52:53]
	s_addc_u32 s31, s31, 0
	s_add_i32 s34, s68, s43
	global_load_lds_dwordx4 v[146:147], off
	v_lshl_add_u64 v[146:147], s[30:31], 0, v[0:1]
	s_mov_b32 m0, s34
	s_nop 0
	global_load_lds_dwordx4 v[146:147], off
	v_lshl_add_u64 v[146:147], s[30:31], 0, v[130:131]
	s_add_i32 m0, s34, 0x2000
	s_nop 0
	global_load_lds_dwordx4 v[146:147], off
	v_lshl_add_u64 v[146:147], v[210:211], 0, s[52:53]
	s_mov_b32 m0, s55
	s_nop 0
	global_load_lds_dwordx4 v[146:147], off
	v_lshl_add_u64 v[146:147], v[212:213], 0, s[52:53]
	s_mov_b32 m0, s56
	s_nop 0
	global_load_lds_dwordx4 v[146:147], off
	s_waitcnt vmcnt(8)
	s_waitcnt lgkmcnt(0)
	s_setprio 1
	s_barrier
	s_waitcnt lgkmcnt(0)
	v_mfma_f32_16x16x32_bf16 v[102:105], v[142:145], v[182:185], v[102:105]
	v_mfma_f32_16x16x32_bf16 v[98:101], v[158:161], v[182:185], v[98:101]
	v_mfma_f32_16x16x32_bf16 v[90:93], v[142:145], v[190:193], v[90:93]
	v_mfma_f32_16x16x32_bf16 v[86:89], v[158:161], v[190:193], v[86:89]
	v_mfma_f32_16x16x32_bf16 v[78:81], v[142:145], v[198:201], v[78:81]
	v_mfma_f32_16x16x32_bf16 v[74:77], v[158:161], v[198:201], v[74:77]
	v_mfma_f32_16x16x32_bf16 v[70:73], v[142:145], v[206:209], v[70:73]
	v_mfma_f32_16x16x32_bf16 v[66:69], v[158:161], v[206:209], v[66:69]
	v_mfma_f32_16x16x32_bf16 v[102:105], v[154:157], v[186:189], v[102:105]
	v_mfma_f32_16x16x32_bf16 v[98:101], v[162:165], v[186:189], v[98:101]
	v_mfma_f32_16x16x32_bf16 v[90:93], v[154:157], v[194:197], v[90:93]
	v_mfma_f32_16x16x32_bf16 v[86:89], v[162:165], v[194:197], v[86:89]
	v_mfma_f32_16x16x32_bf16 v[78:81], v[154:157], v[202:205], v[78:81]
	v_mfma_f32_16x16x32_bf16 v[74:77], v[162:165], v[202:205], v[74:77]
	v_mfma_f32_16x16x32_bf16 v[70:73], v[154:157], v[220:223], v[70:73]
	v_mfma_f32_16x16x32_bf16 v[66:69], v[162:165], v[220:223], v[66:69]
	s_setprio 0
	s_setprio 1
	v_mfma_f32_16x16x32_bf16 v[54:57], v[166:169], v[182:185], v[54:57]
	v_mfma_f32_16x16x32_bf16 v[18:21], v[174:177], v[182:185], v[18:21]
	v_mfma_f32_16x16x32_bf16 v[58:61], v[166:169], v[190:193], v[58:61]
	v_mfma_f32_16x16x32_bf16 v[30:33], v[174:177], v[190:193], v[30:33]
	v_mfma_f32_16x16x32_bf16 v[62:65], v[166:169], v[198:201], v[62:65]
	v_mfma_f32_16x16x32_bf16 v[38:41], v[174:177], v[198:201], v[38:41]
	v_mfma_f32_16x16x32_bf16 v[50:53], v[166:169], v[206:209], v[50:53]
	v_mfma_f32_16x16x32_bf16 v[22:25], v[174:177], v[206:209], v[22:25]
	v_mfma_f32_16x16x32_bf16 v[54:57], v[170:173], v[186:189], v[54:57]
	v_mfma_f32_16x16x32_bf16 v[18:21], v[178:181], v[186:189], v[18:21]
	v_mfma_f32_16x16x32_bf16 v[58:61], v[170:173], v[194:197], v[58:61]
	v_mfma_f32_16x16x32_bf16 v[30:33], v[178:181], v[194:197], v[30:33]
	v_mfma_f32_16x16x32_bf16 v[62:65], v[170:173], v[202:205], v[62:65]
	v_mfma_f32_16x16x32_bf16 v[38:41], v[178:181], v[202:205], v[38:41]
	v_mfma_f32_16x16x32_bf16 v[50:53], v[170:173], v[220:223], v[50:53]
	v_mfma_f32_16x16x32_bf16 v[22:25], v[178:181], v[220:223], v[22:25]
	s_barrier
	s_setprio 0
	s_add_i32 s64, s64, 2
	s_add_u32 s28, s28, 0x100
	s_addc_u32 s29, s29, 0
	s_cmp_gt_u32 s64, 41
	s_cbranch_scc0 .LBB0_382
	s_add_u32 s28, s62, 0xffffff00
	s_addc_u32 s29, s63, -1
	s_and_b64 vcc, exec, s[6:7]
	s_cbranch_vccnz .LBB0_369
	v_mov_b32_e32 v22, 0
	s_mov_b32 s18, s59
	s_mov_b32 s37, s60
	s_mov_b64 s[24:25], s[26:27]
	s_mov_b32 s58, s61
	v_mov_b32_e32 v23, v22
	v_mov_b32_e32 v24, v22
	v_mov_b32_e32 v25, v22
	v_mov_b32_e32 v50, v22
	v_mov_b32_e32 v51, v22
	v_mov_b32_e32 v52, v22
	v_mov_b32_e32 v53, v22
	v_mov_b32_e32 v38, v22
	v_mov_b32_e32 v39, v22
	v_mov_b32_e32 v40, v22
	v_mov_b32_e32 v41, v22
	v_mov_b32_e32 v62, v22
	v_mov_b32_e32 v63, v22
	v_mov_b32_e32 v64, v22
	v_mov_b32_e32 v65, v22
	v_mov_b32_e32 v30, v22
	v_mov_b32_e32 v31, v22
	v_mov_b32_e32 v32, v22
	v_mov_b32_e32 v33, v22
	v_mov_b32_e32 v58, v22
	v_mov_b32_e32 v59, v22
	v_mov_b32_e32 v60, v22
	v_mov_b32_e32 v61, v22
	v_mov_b32_e32 v18, v22
	v_mov_b32_e32 v19, v22
	v_mov_b32_e32 v20, v22
	v_mov_b32_e32 v21, v22
	v_mov_b32_e32 v54, v22
	v_mov_b32_e32 v55, v22
	v_mov_b32_e32 v56, v22
	v_mov_b32_e32 v57, v22
	v_mov_b32_e32 v66, v22
	v_mov_b32_e32 v67, v22
	v_mov_b32_e32 v68, v22
	v_mov_b32_e32 v69, v22
	v_mov_b32_e32 v70, v22
	v_mov_b32_e32 v71, v22
	v_mov_b32_e32 v72, v22
	v_mov_b32_e32 v73, v22
	v_mov_b32_e32 v74, v22
	v_mov_b32_e32 v75, v22
	v_mov_b32_e32 v76, v22
	v_mov_b32_e32 v77, v22
	v_mov_b32_e32 v78, v22
	v_mov_b32_e32 v79, v22
	v_mov_b32_e32 v80, v22
	v_mov_b32_e32 v81, v22
	v_mov_b32_e32 v86, v22
	v_mov_b32_e32 v87, v22
	v_mov_b32_e32 v88, v22
	v_mov_b32_e32 v89, v22
	v_mov_b32_e32 v90, v22
	v_mov_b32_e32 v91, v22
	v_mov_b32_e32 v92, v22
	v_mov_b32_e32 v93, v22
	v_mov_b32_e32 v98, v22
	v_mov_b32_e32 v99, v22
	v_mov_b32_e32 v100, v22
	v_mov_b32_e32 v101, v22
	v_mov_b32_e32 v102, v22
	v_mov_b32_e32 v103, v22
	v_mov_b32_e32 v104, v22
	v_mov_b32_e32 v105, v22
	v_mov_b32_e32 v14, v22
	v_mov_b32_e32 v15, v22
	v_mov_b32_e32 v16, v22
	v_mov_b32_e32 v17, v22
	v_mov_b32_e32 v46, v22
	v_mov_b32_e32 v47, v22
	v_mov_b32_e32 v48, v22
	v_mov_b32_e32 v49, v22
	v_mov_b32_e32 v10, v22
	v_mov_b32_e32 v11, v22
	v_mov_b32_e32 v12, v22
	v_mov_b32_e32 v13, v22
	v_mov_b32_e32 v42, v22
	v_mov_b32_e32 v43, v22
	v_mov_b32_e32 v44, v22
	v_mov_b32_e32 v45, v22
	v_mov_b32_e32 v6, v22
	v_mov_b32_e32 v7, v22
	v_mov_b32_e32 v8, v22
	v_mov_b32_e32 v9, v22
	v_mov_b32_e32 v34, v22
	v_mov_b32_e32 v35, v22
	v_mov_b32_e32 v36, v22
	v_mov_b32_e32 v37, v22
	v_mov_b32_e32 v2, v22
	v_mov_b32_e32 v3, v22
	v_mov_b32_e32 v4, v22
	v_mov_b32_e32 v5, v22
	v_mov_b32_e32 v26, v22
	v_mov_b32_e32 v27, v22
	v_mov_b32_e32 v28, v22
	v_mov_b32_e32 v29, v22
	v_mov_b32_e32 v110, v22
	v_mov_b32_e32 v111, v22
	v_mov_b32_e32 v112, v22
	v_mov_b32_e32 v113, v22
	v_mov_b32_e32 v118, v22
	v_mov_b32_e32 v119, v22
	v_mov_b32_e32 v120, v22
	v_mov_b32_e32 v121, v22
	v_mov_b32_e32 v106, v22
	v_mov_b32_e32 v107, v22
	v_mov_b32_e32 v108, v22
	v_mov_b32_e32 v109, v22
	v_mov_b32_e32 v126, v22
	v_mov_b32_e32 v127, v22
	v_mov_b32_e32 v128, v22
	v_mov_b32_e32 v129, v22
	v_mov_b32_e32 v94, v22
	v_mov_b32_e32 v95, v22
	v_mov_b32_e32 v96, v22
	v_mov_b32_e32 v97, v22
	v_mov_b32_e32 v122, v22
	v_mov_b32_e32 v123, v22
	v_mov_b32_e32 v124, v22
	v_mov_b32_e32 v125, v22
	v_mov_b32_e32 v82, v22
	v_mov_b32_e32 v83, v22
	v_mov_b32_e32 v84, v22
	v_mov_b32_e32 v85, v22
	v_mov_b32_e32 v114, v22
	v_mov_b32_e32 v115, v22
	v_mov_b32_e32 v116, v22
	v_mov_b32_e32 v117, v22
	s_andn2_b64 vcc, exec, s[4:5]
	s_cbranch_vccnz .LBB0_370

; #define PG8_STAGE(bufoff, gbase, voff) do { _Pragma("unroll") for (int _i = 0; _i < 2; ++_i) \
;         __builtin_amdgcn_global_load_lds((const unsigned*)((const char*)(gbase) + (voff)[_i]), (PG8_LAS unsigned*)(lds + (bufoff) + ldsw + _i * 8192), 16, 0, 0); } while (0)
; #define PG8_LDA(dst, b, h) do { _Pragma("unroll") for (int m = 0; m < 4; ++m) _Pragma("unroll") for (int k = 0; k < 2; ++k) dst[m][k] = *(const PG8_LAS bf16x8*)(lds + PG8_SA(b, h) + aoff + m * 2048 + k * 1024); } while (0)
; #define PG8_LDB(dst, b, h) do { _Pragma("unroll") for (int n = 0; n < 2; ++n) _Pragma("unroll") for (int k = 0; k < 2; ++k) dst[n][k] = *(const PG8_LAS bf16x8*)(lds + PG8_SB(b, h) + boff + n * 2048 + k * 1024); } while (0)
; #define PG8_MMA(ai, bj, At, Bt) do { __builtin_amdgcn_s_setprio(1); _Pragma("unroll") for (int m = 0; m < 4; ++m) _Pragma("unroll") for (int n = 0; n < 2; ++n) _Pragma("unroll") for (int k = 0; k < 2; ++k) \
;         acc[ai][bj][m][n] = __builtin_amdgcn_mfma_f32_16x16x32_bf16(Bt[n][k], At[m][k], acc[ai][bj][m][n], 0, 0, 0); __builtin_amdgcn_s_setprio(0); } while (0)
; #define PG8_WAIT_V(n) asm volatile("s_waitcnt vmcnt(" #n ")" ::: "memory")
; #define PG8_WAIT_L(n) asm volatile("s_waitcnt lgkmcnt(" #n ")" ::: "memory")
; #define PG8_BAR __builtin_amdgcn_s_barrier()
; #define PG8_SCHED __builtin_amdgcn_sched_barrier(0)
; template <class Epi, class Sched, bool ALIGN_EPI = false, bool SP2 = false>
; __device__ __forceinline__ void gemm_phase(PG8_LAS unsigned char* lds, const Gemm g, const Sched& S, const Epi& E) {
;     ...
;             const bool last = (t == nt - 2);
;             const char* a1 = cA + (size_t)(t + 1) * kstep;
;             const char* a2 = last ? nA : cA + (size_t)(t + 2) * kstep; const char* b2 = last ? nB : cB + (size_t)(t + 2) * kstep;
;             const char* a3 = a2 + kstep; const char* b3 = b2 + kstep;
;             if (last && has_next) S.a_ready(nxt);
;             if constexpr (SP2) {
;             PG8_LDB(B0, 0, 0); PG8_LDB(B1, 0, 1); PG8_SCHED; PG8_LDA(At, 0, 0); PG8_STAGE(PG8_SA(1, 1), a1 + hstep, voffA);
;             PG8_WAIT_V(8); PG8_WAIT_L(0); PG8_BAR; PG8_MMA(0, 0, At, B0); PG8_MMA(0, 1, At, B1); PG8_BAR; PG8_SCHED;
;             if (full) PG8_LDA(At, 0, 1); PG8_STAGE(PG8_SB(0, 0), b2, voffB); PG8_STAGE(PG8_SB(0, 1), b2 + hstep, voffB); PG8_STAGE(PG8_SA(0, 0), a2, voffA);
.LBB0_521:
	v_add_u32_e32 v0, 0x10000, v225
	ds_read_b128 v[148:151], v0
	ds_read_b128 v[152:155], v0 offset:1024
	ds_read_b128 v[156:159], v0 offset:2048
	ds_read_b128 v[160:163], v0 offset:3072
	v_add_u32_e32 v0, 0x14000, v225
	ds_read_b128 v[132:135], v0
	ds_read_b128 v[136:139], v0 offset:1024
	ds_read_b128 v[140:143], v0 offset:2048
	ds_read_b128 v[144:147], v0 offset:3072
	v_lshl_add_u64 v[2:3], s[34:35], 0, v[204:205]
	s_add_i32 m0, s27, 0xc000
	ds_read_b128 v[176:179], v241
	ds_read_b128 v[192:195], v241 offset:1024
	ds_read_b128 v[172:175], v241 offset:2048
	ds_read_b128 v[188:191], v241 offset:3072
	ds_read_b128 v[168:171], v241 offset:4096
	ds_read_b128 v[184:187], v241 offset:5120
	ds_read_b128 v[164:167], v241 offset:6144
	ds_read_b128 v[180:183], v241 offset:7168
	global_load_lds_dwordx4 v[2:3], off
	v_lshl_add_u64 v[2:3], s[34:35], 0, v[206:207]
	s_add_i32 m0, s27, 0xe000
	s_nop 0
	global_load_lds_dwordx4 v[2:3], off
	s_waitcnt vmcnt(8)
	s_waitcnt lgkmcnt(0)
	s_setprio 1
	s_barrier
	s_waitcnt lgkmcnt(0)
	v_mfma_f32_16x16x32_bf16 v[128:131], v[148:151], v[176:179], v[128:131]
	v_mfma_f32_16x16x32_bf16 v[124:127], v[156:159], v[176:179], v[124:127]
	v_mfma_f32_16x16x32_bf16 v[112:115], v[148:151], v[172:175], v[112:115]
	v_mfma_f32_16x16x32_bf16 v[108:111], v[156:159], v[172:175], v[108:111]
	v_mfma_f32_16x16x32_bf16 v[96:99], v[148:151], v[168:171], v[96:99]
	v_mfma_f32_16x16x32_bf16 v[92:95], v[156:159], v[168:171], v[92:95]
	v_mfma_f32_16x16x32_bf16 v[80:83], v[148:151], v[164:167], v[80:83]
	v_mfma_f32_16x16x32_bf16 v[76:79], v[156:159], v[164:167], v[76:79]
	v_mfma_f32_16x16x32_bf16 v[128:131], v[152:155], v[192:195], v[128:131]
	v_mfma_f32_16x16x32_bf16 v[124:127], v[160:163], v[192:195], v[124:127]
	v_mfma_f32_16x16x32_bf16 v[112:115], v[152:155], v[188:191], v[112:115]
	v_mfma_f32_16x16x32_bf16 v[108:111], v[160:163], v[188:191], v[108:111]
	v_mfma_f32_16x16x32_bf16 v[96:99], v[152:155], v[184:187], v[96:99]
	v_mfma_f32_16x16x32_bf16 v[92:95], v[160:163], v[184:187], v[92:95]
	v_mfma_f32_16x16x32_bf16 v[80:83], v[152:155], v[180:183], v[80:83]
	v_mfma_f32_16x16x32_bf16 v[76:79], v[160:163], v[180:183], v[76:79]
	s_setprio 0
	s_setprio 1
	v_mfma_f32_16x16x32_bf16 v[120:123], v[132:135], v[176:179], v[120:123]
	v_mfma_f32_16x16x32_bf16 v[116:119], v[140:143], v[176:179], v[116:119]
	v_mfma_f32_16x16x32_bf16 v[104:107], v[132:135], v[172:175], v[104:107]
	v_mfma_f32_16x16x32_bf16 v[100:103], v[140:143], v[172:175], v[100:103]
	v_mfma_f32_16x16x32_bf16 v[88:91], v[132:135], v[168:171], v[88:91]
	v_mfma_f32_16x16x32_bf16 v[84:87], v[140:143], v[168:171], v[84:87]
	v_mfma_f32_16x16x32_bf16 v[72:75], v[132:135], v[164:167], v[72:75]
	v_mfma_f32_16x16x32_bf16 v[68:71], v[140:143], v[164:167], v[68:71]
	v_mfma_f32_16x16x32_bf16 v[120:123], v[136:139], v[192:195], v[120:123]
	v_mfma_f32_16x16x32_bf16 v[116:119], v[144:147], v[192:195], v[116:119]
	v_mfma_f32_16x16x32_bf16 v[104:107], v[136:139], v[188:191], v[104:107]
	v_mfma_f32_16x16x32_bf16 v[100:103], v[144:147], v[188:191], v[100:103]
	v_mfma_f32_16x16x32_bf16 v[88:91], v[136:139], v[184:187], v[88:91]
	v_mfma_f32_16x16x32_bf16 v[84:87], v[144:147], v[184:187], v[84:87]
	v_mfma_f32_16x16x32_bf16 v[72:75], v[136:139], v[180:183], v[72:75]
	v_mfma_f32_16x16x32_bf16 v[68:71], v[144:147], v[180:183], v[68:71]
	s_barrier
	s_setprio 0
	v_cndmask_b32_e64 v0, 0, 1, s[30:31]
	v_cmp_ne_u32_e64 s[4:5], 1, v0
	s_andn2_b64 vcc, exec, s[30:31]
	s_cbranch_vccnz .LBB0_523
	ds_read_b128 v[176:179], v241 offset:16384
	ds_read_b128 v[192:195], v241 offset:17408
	ds_read_b128 v[172:175], v241 offset:18432
	ds_read_b128 v[188:191], v241 offset:19456
	ds_read_b128 v[168:171], v241 offset:20480
	ds_read_b128 v[184:187], v241 offset:21504
	ds_read_b128 v[164:167], v241 offset:22528
	ds_read_b128 v[180:183], v241 offset:23552
.LBB0_523:
	s_add_u32 s36, s34, 0xfffc0080
	s_addc_u32 s37, s35, -1
	s_cmp_eq_u32 s82, 12
	s_cselect_b32 s39, s1, s37
	s_cselect_b32 s38, s19, s36
	s_cselect_b32 s37, s17, s81
	s_cselect_b32 s36, s29, s80
	s_mov_b32 m0, s49
	v_lshl_add_u64 v[2:3], s[36:37], 0, v[198:199]
	s_add_u32 s88, s36, 0x40000
	global_load_lds_dwordx4 v[2:3], off
	v_lshl_add_u64 v[208:209], s[36:37], 0, v[202:203]
	s_mov_b32 m0, s54
	s_addc_u32 s89, s37, 0
	global_load_lds_dwordx4 v[208:209], off
	v_lshl_add_u64 v[210:211], s[88:89], 0, v[198:199]
	s_mov_b32 m0, s55
	v_lshl_add_u64 v[220:221], s[38:39], 0, v[200:201]
	global_load_lds_dwordx4 v[210:211], off
	v_lshl_add_u64 v[210:211], s[88:89], 0, v[202:203]
	s_mov_b32 m0, s56
	s_and_b64 vcc, exec, s[4:5]
	global_load_lds_dwordx4 v[210:211], off
	v_lshl_add_u64 v[210:211], s[38:39], 0, v[196:197]
	s_mov_b32 m0, s27
	s_nop 0
	global_load_lds_dwordx4 v[210:211], off
	s_mov_b32 m0, s57
	s_nop 0
	global_load_lds_dwordx4 v[220:221], off
	s_waitcnt vmcnt(8)
	s_waitcnt lgkmcnt(0)
	s_setprio 1
	s_barrier
	s_cbranch_vccnz .LBB0_525
; #define PG8_STAGE(bufoff, gbase, voff) do { _Pragma("unroll") for (int _i = 0; _i < 2; ++_i) \
;         __builtin_amdgcn_global_load_lds((const unsigned*)((const char*)(gbase) + (voff)[_i]), (PG8_LAS unsigned*)(lds + (bufoff) + ldsw + _i * 8192), 16, 0, 0); } while (0)
; #define PG8_LDA(dst, b, h) do { _Pragma("unroll") for (int m = 0; m < 4; ++m) _Pragma("unroll") for (int k = 0; k < 2; ++k) dst[m][k] = *(const PG8_LAS bf16x8*)(lds + PG8_SA(b, h) + aoff + m * 2048 + k * 1024); } while (0)
; #define PG8_LDB(dst, b, h) do { _Pragma("unroll") for (int n = 0; n < 2; ++n) _Pragma("unroll") for (int k = 0; k < 2; ++k) dst[n][k] = *(const PG8_LAS bf16x8*)(lds + PG8_SB(b, h) + boff + n * 2048 + k * 1024); } while (0)
; #define PG8_MMA(ai, bj, At, Bt) do { __builtin_amdgcn_s_setprio(1); _Pragma("unroll") for (int m = 0; m < 4; ++m) _Pragma("unroll") for (int n = 0; n < 2; ++n) _Pragma("unroll") for (int k = 0; k < 2; ++k) \
;         acc[ai][bj][m][n] = __builtin_amdgcn_mfma_f32_16x16x32_bf16(Bt[n][k], At[m][k], acc[ai][bj][m][n], 0, 0, 0); __builtin_amdgcn_s_setprio(0); } while (0)
; #define PG8_WAIT_V(n) asm volatile("s_waitcnt vmcnt(" #n ")" ::: "memory")
; #define PG8_WAIT_L(n) asm volatile("s_waitcnt lgkmcnt(" #n ")" ::: "memory")
; #define PG8_BAR __builtin_amdgcn_s_barrier()
; #define PG8_SCHED __builtin_amdgcn_sched_barrier(0)
; template <class Epi, class Sched, bool ALIGN_EPI = false, bool SP2 = false>
; __device__ __forceinline__ void gemm_phase(PG8_LAS unsigned char* lds, const Gemm g, const Sched& S, const Epi& E) {
;     ...
;             PG8_WAIT_V(8); PG8_WAIT_L(0); PG8_BAR; if (full) { PG8_MMA(1, 0, At, B0); PG8_MMA(1, 1, At, B1); } PG8_BAR; PG8_SCHED;
;             PG8_LDB(B0, 1, 0); PG8_LDB(B1, 1, 1); PG8_SCHED; PG8_LDA(At, 1, 0); PG8_STAGE(PG8_SA(0, 1), a2 + hstep, voffA);
;             PG8_WAIT_V(8); PG8_WAIT_L(0); PG8_BAR; PG8_MMA(0, 0, At, B0); PG8_MMA(0, 1, At, B1); PG8_BAR; PG8_SCHED;
	s_setprio 1
	s_waitcnt lgkmcnt(0)
	v_mfma_f32_16x16x32_bf16 v[64:67], v[148:151], v[176:179], v[64:67]
	v_mfma_f32_16x16x32_bf16 v[60:63], v[156:159], v[176:179], v[60:63]
	v_mfma_f32_16x16x32_bf16 v[48:51], v[148:151], v[172:175], v[48:51]
	v_mfma_f32_16x16x32_bf16 v[44:47], v[156:159], v[172:175], v[44:47]
	v_mfma_f32_16x16x32_bf16 v[32:35], v[148:151], v[168:171], v[32:35]
	v_mfma_f32_16x16x32_bf16 v[28:31], v[156:159], v[168:171], v[28:31]
	v_mfma_f32_16x16x32_bf16 v[16:19], v[148:151], v[164:167], v[16:19]
	v_mfma_f32_16x16x32_bf16 v[12:15], v[156:159], v[164:167], v[12:15]
	v_mfma_f32_16x16x32_bf16 v[64:67], v[152:155], v[192:195], v[64:67]
	v_mfma_f32_16x16x32_bf16 v[60:63], v[160:163], v[192:195], v[60:63]
	v_mfma_f32_16x16x32_bf16 v[48:51], v[152:155], v[188:191], v[48:51]
	v_mfma_f32_16x16x32_bf16 v[44:47], v[160:163], v[188:191], v[44:47]
	v_mfma_f32_16x16x32_bf16 v[32:35], v[152:155], v[184:187], v[32:35]
	v_mfma_f32_16x16x32_bf16 v[28:31], v[160:163], v[184:187], v[28:31]
	v_mfma_f32_16x16x32_bf16 v[16:19], v[152:155], v[180:183], v[16:19]
	v_mfma_f32_16x16x32_bf16 v[12:15], v[160:163], v[180:183], v[12:15]
	s_setprio 0
	s_setprio 1
	v_mfma_f32_16x16x32_bf16 v[56:59], v[132:135], v[176:179], v[56:59]
	v_mfma_f32_16x16x32_bf16 v[52:55], v[140:143], v[176:179], v[52:55]
	v_mfma_f32_16x16x32_bf16 v[40:43], v[132:135], v[172:175], v[40:43]
	v_mfma_f32_16x16x32_bf16 v[36:39], v[140:143], v[172:175], v[36:39]
	v_mfma_f32_16x16x32_bf16 v[24:27], v[132:135], v[168:171], v[24:27]
	v_mfma_f32_16x16x32_bf16 v[20:23], v[140:143], v[168:171], v[20:23]
	v_mfma_f32_16x16x32_bf16 v[8:11], v[132:135], v[164:167], v[8:11]
	v_mfma_f32_16x16x32_bf16 v[4:7], v[140:143], v[164:167], v[4:7]
	v_mfma_f32_16x16x32_bf16 v[56:59], v[136:139], v[192:195], v[56:59]
	v_mfma_f32_16x16x32_bf16 v[52:55], v[144:147], v[192:195], v[52:55]
	v_mfma_f32_16x16x32_bf16 v[40:43], v[136:139], v[188:191], v[40:43]
	v_mfma_f32_16x16x32_bf16 v[36:39], v[144:147], v[188:191], v[36:39]
	v_mfma_f32_16x16x32_bf16 v[24:27], v[136:139], v[184:187], v[24:27]
	v_mfma_f32_16x16x32_bf16 v[20:23], v[144:147], v[184:187], v[20:23]
	v_mfma_f32_16x16x32_bf16 v[8:11], v[136:139], v[180:183], v[8:11]
	v_mfma_f32_16x16x32_bf16 v[4:7], v[144:147], v[180:183], v[4:7]
.LBB0_525:
	s_barrier
	s_setprio 0
	v_add_u32_e32 v0, 0x18000, v225
	ds_read_b128 v[148:151], v0
	ds_read_b128 v[152:155], v0 offset:1024
	ds_read_b128 v[156:159], v0 offset:2048
	ds_read_b128 v[160:163], v0 offset:3072
	v_add_u32_e32 v0, 0x1c000, v225
	ds_read_b128 v[132:135], v0
	ds_read_b128 v[136:139], v0 offset:1024
	ds_read_b128 v[140:143], v0 offset:2048
	ds_read_b128 v[144:147], v0 offset:3072
	s_add_u32 s38, s38, 0x40000
	s_addc_u32 s39, s39, 0
	s_mov_b32 m0, s58
	v_lshl_add_u64 v[212:213], s[38:39], 0, v[196:197]
	ds_read_b128 v[176:179], v241 offset:32768
	ds_read_b128 v[192:195], v241 offset:33792
	ds_read_b128 v[172:175], v241 offset:34816
	ds_read_b128 v[188:191], v241 offset:35840
	ds_read_b128 v[168:171], v241 offset:36864
	ds_read_b128 v[184:187], v241 offset:37888
	ds_read_b128 v[164:167], v241 offset:38912
	ds_read_b128 v[180:183], v241 offset:39936
	global_load_lds_dwordx4 v[212:213], off
	v_lshl_add_u64 v[212:213], s[38:39], 0, v[200:201]
	s_mov_b32 m0, s59
	s_nop 0
	global_load_lds_dwordx4 v[212:213], off
	s_waitcnt vmcnt(8)
	s_waitcnt lgkmcnt(0)
	s_setprio 1
	s_barrier
	s_waitcnt lgkmcnt(0)
	v_mfma_f32_16x16x32_bf16 v[128:131], v[148:151], v[176:179], v[128:131]
	v_mfma_f32_16x16x32_bf16 v[124:127], v[156:159], v[176:179], v[124:127]
	v_mfma_f32_16x16x32_bf16 v[112:115], v[148:151], v[172:175], v[112:115]
	v_mfma_f32_16x16x32_bf16 v[108:111], v[156:159], v[172:175], v[108:111]
	v_mfma_f32_16x16x32_bf16 v[96:99], v[148:151], v[168:171], v[96:99]
	v_mfma_f32_16x16x32_bf16 v[92:95], v[156:159], v[168:171], v[92:95]
	v_mfma_f32_16x16x32_bf16 v[80:83], v[148:151], v[164:167], v[80:83]
	v_mfma_f32_16x16x32_bf16 v[76:79], v[156:159], v[164:167], v[76:79]
	v_mfma_f32_16x16x32_bf16 v[128:131], v[152:155], v[192:195], v[128:131]
	v_mfma_f32_16x16x32_bf16 v[124:127], v[160:163], v[192:195], v[124:127]
	v_mfma_f32_16x16x32_bf16 v[112:115], v[152:155], v[188:191], v[112:115]
	v_mfma_f32_16x16x32_bf16 v[108:111], v[160:163], v[188:191], v[108:111]
	v_mfma_f32_16x16x32_bf16 v[96:99], v[152:155], v[184:187], v[96:99]
	v_mfma_f32_16x16x32_bf16 v[92:95], v[160:163], v[184:187], v[92:95]
	v_mfma_f32_16x16x32_bf16 v[80:83], v[152:155], v[180:183], v[80:83]
	v_mfma_f32_16x16x32_bf16 v[76:79], v[160:163], v[180:183], v[76:79]
	s_setprio 0
	s_setprio 1
	v_mfma_f32_16x16x32_bf16 v[120:123], v[132:135], v[176:179], v[120:123]
	v_mfma_f32_16x16x32_bf16 v[116:119], v[140:143], v[176:179], v[116:119]
	v_mfma_f32_16x16x32_bf16 v[104:107], v[132:135], v[172:175], v[104:107]
	v_mfma_f32_16x16x32_bf16 v[100:103], v[140:143], v[172:175], v[100:103]
	v_mfma_f32_16x16x32_bf16 v[88:91], v[132:135], v[168:171], v[88:91]
	v_mfma_f32_16x16x32_bf16 v[84:87], v[140:143], v[168:171], v[84:87]
	v_mfma_f32_16x16x32_bf16 v[72:75], v[132:135], v[164:167], v[72:75]
	v_mfma_f32_16x16x32_bf16 v[68:71], v[140:143], v[164:167], v[68:71]
	v_mfma_f32_16x16x32_bf16 v[120:123], v[136:139], v[192:195], v[120:123]
	v_mfma_f32_16x16x32_bf16 v[116:119], v[144:147], v[192:195], v[116:119]
	v_mfma_f32_16x16x32_bf16 v[104:107], v[136:139], v[188:191], v[104:107]
	v_mfma_f32_16x16x32_bf16 v[100:103], v[144:147], v[188:191], v[100:103]
	v_mfma_f32_16x16x32_bf16 v[88:91], v[136:139], v[184:187], v[88:91]
	v_mfma_f32_16x16x32_bf16 v[84:87], v[144:147], v[184:187], v[84:87]
	v_mfma_f32_16x16x32_bf16 v[72:75], v[136:139], v[180:183], v[72:75]
	v_mfma_f32_16x16x32_bf16 v[68:71], v[144:147], v[180:183], v[68:71]
	s_barrier
	s_setprio 0
	s_and_b64 vcc, exec, s[4:5]
	s_cbranch_vccnz .LBB0_527
	ds_read_b128 v[176:179], v241 offset:49152
	ds_read_b128 v[192:195], v241 offset:50176
	ds_read_b128 v[172:175], v241 offset:51200
	ds_read_b128 v[188:191], v241 offset:52224
	ds_read_b128 v[168:171], v241 offset:53248
	ds_read_b128 v[184:187], v241 offset:54272
	ds_read_b128 v[164:167], v241 offset:55296
	ds_read_b128 v[180:183], v241 offset:56320
; #define PG8_STAGE(bufoff, gbase, voff) do { _Pragma("unroll") for (int _i = 0; _i < 2; ++_i) \
;         __builtin_amdgcn_global_load_lds((const unsigned*)((const char*)(gbase) + (voff)[_i]), (PG8_LAS unsigned*)(lds + (bufoff) + ldsw + _i * 8192), 16, 0, 0); } while (0)
; #define PG8_LDA(dst, b, h) do { _Pragma("unroll") for (int m = 0; m < 4; ++m) _Pragma("unroll") for (int k = 0; k < 2; ++k) dst[m][k] = *(const PG8_LAS bf16x8*)(lds + PG8_SA(b, h) + aoff + m * 2048 + k * 1024); } while (0)
; #define PG8_MMA(ai, bj, At, Bt) do { __builtin_amdgcn_s_setprio(1); _Pragma("unroll") for (int m = 0; m < 4; ++m) _Pragma("unroll") for (int n = 0; n < 2; ++n) _Pragma("unroll") for (int k = 0; k < 2; ++k) \
;         acc[ai][bj][m][n] = __builtin_amdgcn_mfma_f32_16x16x32_bf16(Bt[n][k], At[m][k], acc[ai][bj][m][n], 0, 0, 0); __builtin_amdgcn_s_setprio(0); } while (0)
; #define PG8_WAIT_V(n) asm volatile("s_waitcnt vmcnt(" #n ")" ::: "memory")
; #define PG8_WAIT_L(n) asm volatile("s_waitcnt lgkmcnt(" #n ")" ::: "memory")
; #define PG8_BAR __builtin_amdgcn_s_barrier()
; #define PG8_SCHED __builtin_amdgcn_sched_barrier(0)
; template <class Epi, class Sched, bool ALIGN_EPI = false, bool SP2 = false>
; __device__ __forceinline__ void gemm_phase(PG8_LAS unsigned char* lds, const Gemm g, const Sched& S, const Epi& E) {
;     ...
;             if (full) PG8_LDA(At, 1, 1); PG8_STAGE(PG8_SB(1, 0), b3, voffB); PG8_STAGE(PG8_SB(1, 1), b3 + hstep, voffB); PG8_STAGE(PG8_SA(1, 0), a3, voffA);
;             PG8_WAIT_V(8); PG8_WAIT_L(0); PG8_BAR; if (full) { PG8_MMA(1, 0, At, B0); PG8_MMA(1, 1, At, B1); } PG8_BAR; PG8_SCHED;
.LBB0_527:
	s_mov_b32 m0, s62
	v_lshl_add_u64 v[2:3], v[2:3], 0, s[52:53]
	s_add_u32 s36, s36, 0x40080
	global_load_lds_dwordx4 v[2:3], off
	v_lshl_add_u64 v[2:3], v[208:209], 0, s[52:53]
	s_mov_b32 m0, s63
	s_addc_u32 s37, s37, 0
	global_load_lds_dwordx4 v[2:3], off
	v_lshl_add_u64 v[2:3], s[36:37], 0, v[198:199]
	s_mov_b32 m0, s68
	s_and_b64 vcc, exec, s[4:5]
	global_load_lds_dwordx4 v[2:3], off
	v_lshl_add_u64 v[2:3], s[36:37], 0, v[202:203]
	s_mov_b32 m0, s69
	s_nop 0
	global_load_lds_dwordx4 v[2:3], off
	v_lshl_add_u64 v[2:3], v[210:211], 0, s[52:53]
	s_mov_b32 m0, s64
	s_nop 0
	global_load_lds_dwordx4 v[2:3], off
	v_lshl_add_u64 v[2:3], v[220:221], 0, s[52:53]
	s_mov_b32 m0, s65
	s_nop 0
	global_load_lds_dwordx4 v[2:3], off
	s_waitcnt vmcnt(8)
	s_waitcnt lgkmcnt(0)
	s_setprio 1
	s_barrier
	s_cbranch_vccnz .LBB0_520
	s_setprio 1
	s_waitcnt lgkmcnt(0)
	v_mfma_f32_16x16x32_bf16 v[64:67], v[148:151], v[176:179], v[64:67]
	v_mfma_f32_16x16x32_bf16 v[60:63], v[156:159], v[176:179], v[60:63]
	v_mfma_f32_16x16x32_bf16 v[48:51], v[148:151], v[172:175], v[48:51]
	v_mfma_f32_16x16x32_bf16 v[44:47], v[156:159], v[172:175], v[44:47]
	v_mfma_f32_16x16x32_bf16 v[32:35], v[148:151], v[168:171], v[32:35]
	v_mfma_f32_16x16x32_bf16 v[28:31], v[156:159], v[168:171], v[28:31]
	v_mfma_f32_16x16x32_bf16 v[16:19], v[148:151], v[164:167], v[16:19]
	v_mfma_f32_16x16x32_bf16 v[12:15], v[156:159], v[164:167], v[12:15]
	v_mfma_f32_16x16x32_bf16 v[64:67], v[152:155], v[192:195], v[64:67]
	v_mfma_f32_16x16x32_bf16 v[60:63], v[160:163], v[192:195], v[60:63]
	v_mfma_f32_16x16x32_bf16 v[48:51], v[152:155], v[188:191], v[48:51]
	v_mfma_f32_16x16x32_bf16 v[44:47], v[160:163], v[188:191], v[44:47]
	v_mfma_f32_16x16x32_bf16 v[32:35], v[152:155], v[184:187], v[32:35]
	v_mfma_f32_16x16x32_bf16 v[28:31], v[160:163], v[184:187], v[28:31]
	v_mfma_f32_16x16x32_bf16 v[16:19], v[152:155], v[180:183], v[16:19]
	v_mfma_f32_16x16x32_bf16 v[12:15], v[160:163], v[180:183], v[12:15]
	s_setprio 0
	s_setprio 1
	v_mfma_f32_16x16x32_bf16 v[56:59], v[132:135], v[176:179], v[56:59]
	v_mfma_f32_16x16x32_bf16 v[52:55], v[140:143], v[176:179], v[52:55]
	v_mfma_f32_16x16x32_bf16 v[40:43], v[132:135], v[172:175], v[40:43]
	v_mfma_f32_16x16x32_bf16 v[36:39], v[140:143], v[172:175], v[36:39]
	v_mfma_f32_16x16x32_bf16 v[24:27], v[132:135], v[168:171], v[24:27]
	v_mfma_f32_16x16x32_bf16 v[20:23], v[140:143], v[168:171], v[20:23]
	v_mfma_f32_16x16x32_bf16 v[8:11], v[132:135], v[164:167], v[8:11]
	v_mfma_f32_16x16x32_bf16 v[2:5], v[140:143], v[164:167], v[4:7]
	v_mfma_f32_16x16x32_bf16 v[56:59], v[136:139], v[192:195], v[56:59]
	v_mfma_f32_16x16x32_bf16 v[52:55], v[144:147], v[192:195], v[52:55]
	v_mfma_f32_16x16x32_bf16 v[40:43], v[136:139], v[188:191], v[40:43]
	v_mfma_f32_16x16x32_bf16 v[36:39], v[144:147], v[188:191], v[36:39]
	v_mfma_f32_16x16x32_bf16 v[24:27], v[136:139], v[184:187], v[24:27]
	v_mfma_f32_16x16x32_bf16 v[20:23], v[144:147], v[184:187], v[20:23]
	v_mfma_f32_16x16x32_bf16 v[8:11], v[136:139], v[180:183], v[8:11]
	v_mfma_f32_16x16x32_bf16 v[4:7], v[144:147], v[180:183], v[2:5]
	s_branch .LBB0_520

; #define PG8_STAGE(bufoff, gbase, voff) do { _Pragma("unroll") for (int _i = 0; _i < 2; ++_i) \
;         __builtin_amdgcn_global_load_lds((const unsigned*)((const char*)(gbase) + (voff)[_i]), (PG8_LAS unsigned*)(lds + (bufoff) + ldsw + _i * 8192), 16, 0, 0); } while (0)
; #define PG8_LDA(dst, b, h) do { _Pragma("unroll") for (int m = 0; m < 4; ++m) _Pragma("unroll") for (int k = 0; k < 2; ++k) dst[m][k] = *(const PG8_LAS bf16x8*)(lds + PG8_SA(b, h) + aoff + m * 2048 + k * 1024); } while (0)
; #define PG8_LDB(dst, b, h) do { _Pragma("unroll") for (int n = 0; n < 2; ++n) _Pragma("unroll") for (int k = 0; k < 2; ++k) dst[n][k] = *(const PG8_LAS bf16x8*)(lds + PG8_SB(b, h) + boff + n * 2048 + k * 1024); } while (0)
; #define PG8_MMA(ai, bj, At, Bt) do { __builtin_amdgcn_s_setprio(1); _Pragma("unroll") for (int m = 0; m < 4; ++m) _Pragma("unroll") for (int n = 0; n < 2; ++n) _Pragma("unroll") for (int k = 0; k < 2; ++k) \
;         acc[ai][bj][m][n] = __builtin_amdgcn_mfma_f32_16x16x32_bf16(Bt[n][k], At[m][k], acc[ai][bj][m][n], 0, 0, 0); __builtin_amdgcn_s_setprio(0); } while (0)
; #define PG8_WAIT_V(n) asm volatile("s_waitcnt vmcnt(" #n ")" ::: "memory")
; #define PG8_WAIT_L(n) asm volatile("s_waitcnt lgkmcnt(" #n ")" ::: "memory")
; #define PG8_BAR __builtin_amdgcn_s_barrier()
; #define PG8_SCHED __builtin_amdgcn_sched_barrier(0)
; template <class Epi, class Sched, bool ALIGN_EPI = false, bool SP2 = false>
; __device__ __forceinline__ void gemm_phase(PG8_LAS unsigned char* lds, const Gemm g, const Sched& S, const Epi& E) {
;     ...
;             const bool last = (t == nt - 2);
;             const char* a1 = cA + (size_t)(t + 1) * kstep;
;             const char* a2 = last ? nA : cA + (size_t)(t + 2) * kstep; const char* b2 = last ? nB : cB + (size_t)(t + 2) * kstep;
;             const char* a3 = a2 + kstep; const char* b3 = b2 + kstep;
;             if (last && has_next) S.a_ready(nxt);
;             if constexpr (SP2) {
;             PG8_LDB(B0, 0, 0); PG8_LDB(B1, 0, 1); PG8_SCHED; PG8_LDA(At, 0, 0); PG8_STAGE(PG8_SA(1, 1), a1 + hstep, voffA);
;             PG8_WAIT_V(8); PG8_WAIT_L(0); PG8_BAR; PG8_MMA(0, 0, At, B0); PG8_MMA(0, 1, At, B1); PG8_BAR; PG8_SCHED;
;             if (full) PG8_LDA(At, 0, 1); PG8_STAGE(PG8_SB(0, 0), b2, voffB); PG8_STAGE(PG8_SB(0, 1), b2 + hstep, voffB); PG8_STAGE(PG8_SA(0, 0), a2, voffA);
.LBB0_1038:
	s_add_u32 s27, s6, 0xfffe0080
	s_addc_u32 s28, s7, -1
	s_add_i32 s54, 0, 0x10000
	s_cmp_eq_u32 s25, 4
	s_cselect_b32 s31, s21, s28
	s_cselect_b32 s30, s20, s27
	v_add_u32_e32 v0, s54, v179
	s_cselect_b32 s29, s0, s19
	s_cselect_b32 s28, s1, s17
	s_add_i32 s27, 0, 0x14000
	ds_read_b128 v[144:147], v0
	ds_read_b128 v[148:151], v0 offset:1024
	ds_read_b128 v[152:155], v0 offset:2048
	ds_read_b128 v[156:159], v0 offset:3072
	v_add_u32_e32 v0, s27, v179
	ds_read_b128 v[160:163], v0
	ds_read_b128 v[164:167], v0 offset:1024
	ds_read_b128 v[168:171], v0 offset:2048
	ds_read_b128 v[172:175], v0 offset:3072
	v_lshl_add_u64 v[2:3], s[6:7], 0, v[140:141]
	s_add_i32 m0, s39, 0xc000
	ds_read_b128 v[182:185], v181
	ds_read_b128 v[186:189], v181 offset:1024
	ds_read_b128 v[190:193], v181 offset:2048
	ds_read_b128 v[194:197], v181 offset:3072
	ds_read_b128 v[198:201], v181 offset:4096
	ds_read_b128 v[202:205], v181 offset:5120
	ds_read_b128 v[206:209], v181 offset:6144
	ds_read_b128 v[220:223], v181 offset:7168
	global_load_lds_dwordx4 v[2:3], off
	v_lshl_add_u64 v[2:3], s[6:7], 0, v[142:143]
	s_add_i32 m0, s39, 0xe000
	s_nop 0
	global_load_lds_dwordx4 v[2:3], off
	s_waitcnt vmcnt(8)
	s_waitcnt lgkmcnt(0)
	s_setprio 1
	s_barrier
	s_waitcnt lgkmcnt(0)
	v_mfma_f32_16x16x32_bf16 v[128:131], v[144:147], v[182:185], v[128:131]
	v_mfma_f32_16x16x32_bf16 v[124:127], v[152:155], v[182:185], v[124:127]
	v_mfma_f32_16x16x32_bf16 v[120:123], v[144:147], v[190:193], v[120:123]
	v_mfma_f32_16x16x32_bf16 v[116:119], v[152:155], v[190:193], v[116:119]
	v_mfma_f32_16x16x32_bf16 v[112:115], v[144:147], v[198:201], v[112:115]
	v_mfma_f32_16x16x32_bf16 v[108:111], v[152:155], v[198:201], v[108:111]
	v_mfma_f32_16x16x32_bf16 v[104:107], v[144:147], v[206:209], v[104:107]
	v_mfma_f32_16x16x32_bf16 v[100:103], v[152:155], v[206:209], v[100:103]
	v_mfma_f32_16x16x32_bf16 v[128:131], v[148:151], v[186:189], v[128:131]
	v_mfma_f32_16x16x32_bf16 v[124:127], v[156:159], v[186:189], v[124:127]
	v_mfma_f32_16x16x32_bf16 v[120:123], v[148:151], v[194:197], v[120:123]
	v_mfma_f32_16x16x32_bf16 v[116:119], v[156:159], v[194:197], v[116:119]
	v_mfma_f32_16x16x32_bf16 v[112:115], v[148:151], v[202:205], v[112:115]
	v_mfma_f32_16x16x32_bf16 v[108:111], v[156:159], v[202:205], v[108:111]
	v_mfma_f32_16x16x32_bf16 v[104:107], v[148:151], v[220:223], v[104:107]
	v_mfma_f32_16x16x32_bf16 v[100:103], v[156:159], v[220:223], v[100:103]
	s_setprio 0
	s_setprio 1
	v_mfma_f32_16x16x32_bf16 v[96:99], v[160:163], v[182:185], v[96:99]
	v_mfma_f32_16x16x32_bf16 v[92:95], v[168:171], v[182:185], v[92:95]
	v_mfma_f32_16x16x32_bf16 v[88:91], v[160:163], v[190:193], v[88:91]
	v_mfma_f32_16x16x32_bf16 v[84:87], v[168:171], v[190:193], v[84:87]
	v_mfma_f32_16x16x32_bf16 v[80:83], v[160:163], v[198:201], v[80:83]
	v_mfma_f32_16x16x32_bf16 v[76:79], v[168:171], v[198:201], v[76:79]
	v_mfma_f32_16x16x32_bf16 v[72:75], v[160:163], v[206:209], v[72:75]
	v_mfma_f32_16x16x32_bf16 v[68:71], v[168:171], v[206:209], v[68:71]
	v_mfma_f32_16x16x32_bf16 v[96:99], v[164:167], v[186:189], v[96:99]
	v_mfma_f32_16x16x32_bf16 v[92:95], v[172:175], v[186:189], v[92:95]
	v_mfma_f32_16x16x32_bf16 v[88:91], v[164:167], v[194:197], v[88:91]
	v_mfma_f32_16x16x32_bf16 v[84:87], v[172:175], v[194:197], v[84:87]
	v_mfma_f32_16x16x32_bf16 v[80:83], v[164:167], v[202:205], v[80:83]
	v_mfma_f32_16x16x32_bf16 v[76:79], v[172:175], v[202:205], v[76:79]
	v_mfma_f32_16x16x32_bf16 v[72:75], v[164:167], v[220:223], v[72:75]
	v_mfma_f32_16x16x32_bf16 v[68:71], v[172:175], v[220:223], v[68:71]
	s_barrier
	s_setprio 0
	s_add_i32 s54, s54, s38
	v_lshl_add_u64 v[176:177], s[28:29], 0, v[134:135]
	s_mov_b32 m0, s54
	ds_read_b128 v[182:185], v181 offset:16384
	ds_read_b128 v[186:189], v181 offset:17408
	ds_read_b128 v[190:193], v181 offset:18432
	ds_read_b128 v[194:197], v181 offset:19456
	ds_read_b128 v[198:201], v181 offset:20480
	ds_read_b128 v[202:205], v181 offset:21504
	ds_read_b128 v[206:209], v181 offset:22528
	ds_read_b128 v[220:223], v181 offset:23552
	global_load_lds_dwordx4 v[176:177], off
	s_add_i32 m0, s54, 0x2000
	s_add_u32 s54, s28, 0x20000
	v_lshl_add_u64 v[210:211], s[28:29], 0, v[138:139]
	s_addc_u32 s55, s29, 0
	s_add_i32 s27, s27, s38
	global_load_lds_dwordx4 v[210:211], off
	v_lshl_add_u64 v[2:3], s[54:55], 0, v[134:135]
	s_mov_b32 m0, s27
	v_lshl_add_u64 v[212:213], s[30:31], 0, v[132:133]
	global_load_lds_dwordx4 v[2:3], off
	v_lshl_add_u64 v[2:3], s[54:55], 0, v[138:139]
	s_add_i32 m0, s27, 0x2000
	v_lshl_add_u64 v[214:215], s[30:31], 0, v[136:137]
	global_load_lds_dwordx4 v[2:3], off
	s_mov_b32 m0, s39
	s_nop 0
	global_load_lds_dwordx4 v[212:213], off
	s_mov_b32 m0, s40
	s_nop 0
	global_load_lds_dwordx4 v[214:215], off
	s_waitcnt vmcnt(8)
	s_waitcnt lgkmcnt(0)
	s_setprio 1
	s_barrier
; #define PG8_STAGE(bufoff, gbase, voff) do { _Pragma("unroll") for (int _i = 0; _i < 2; ++_i) \
;         __builtin_amdgcn_global_load_lds((const unsigned*)((const char*)(gbase) + (voff)[_i]), (PG8_LAS unsigned*)(lds + (bufoff) + ldsw + _i * 8192), 16, 0, 0); } while (0)
; #define PG8_LDA(dst, b, h) do { _Pragma("unroll") for (int m = 0; m < 4; ++m) _Pragma("unroll") for (int k = 0; k < 2; ++k) dst[m][k] = *(const PG8_LAS bf16x8*)(lds + PG8_SA(b, h) + aoff + m * 2048 + k * 1024); } while (0)
; #define PG8_LDB(dst, b, h) do { _Pragma("unroll") for (int n = 0; n < 2; ++n) _Pragma("unroll") for (int k = 0; k < 2; ++k) dst[n][k] = *(const PG8_LAS bf16x8*)(lds + PG8_SB(b, h) + boff + n * 2048 + k * 1024); } while (0)
; #define PG8_MMA(ai, bj, At, Bt) do { __builtin_amdgcn_s_setprio(1); _Pragma("unroll") for (int m = 0; m < 4; ++m) _Pragma("unroll") for (int n = 0; n < 2; ++n) _Pragma("unroll") for (int k = 0; k < 2; ++k) \
;         acc[ai][bj][m][n] = __builtin_amdgcn_mfma_f32_16x16x32_bf16(Bt[n][k], At[m][k], acc[ai][bj][m][n], 0, 0, 0); __builtin_amdgcn_s_setprio(0); } while (0)
; #define PG8_WAIT_V(n) asm volatile("s_waitcnt vmcnt(" #n ")" ::: "memory")
; #define PG8_WAIT_L(n) asm volatile("s_waitcnt lgkmcnt(" #n ")" ::: "memory")
; #define PG8_BAR __builtin_amdgcn_s_barrier()
; #define PG8_SCHED __builtin_amdgcn_sched_barrier(0)
; template <class Epi, class Sched, bool ALIGN_EPI = false, bool SP2 = false>
; __device__ __forceinline__ void gemm_phase(PG8_LAS unsigned char* lds, const Gemm g, const Sched& S, const Epi& E) {
;     ...
;             PG8_WAIT_V(8); PG8_WAIT_L(0); PG8_BAR; if (full) { PG8_MMA(1, 0, At, B0); PG8_MMA(1, 1, At, B1); } PG8_BAR; PG8_SCHED;
;             PG8_LDB(B0, 1, 0); PG8_LDB(B1, 1, 1); PG8_SCHED; PG8_LDA(At, 1, 0); PG8_STAGE(PG8_SA(0, 1), a2 + hstep, voffA);
;             PG8_WAIT_V(8); PG8_WAIT_L(0); PG8_BAR; PG8_MMA(0, 0, At, B0); PG8_MMA(0, 1, At, B1); PG8_BAR; PG8_SCHED;
	s_waitcnt lgkmcnt(0)
	v_mfma_f32_16x16x32_bf16 v[64:67], v[144:147], v[182:185], v[64:67]
	v_mfma_f32_16x16x32_bf16 v[60:63], v[152:155], v[182:185], v[60:63]
	v_mfma_f32_16x16x32_bf16 v[56:59], v[144:147], v[190:193], v[56:59]
	v_mfma_f32_16x16x32_bf16 v[52:55], v[152:155], v[190:193], v[52:55]
	v_mfma_f32_16x16x32_bf16 v[48:51], v[144:147], v[198:201], v[48:51]
	v_mfma_f32_16x16x32_bf16 v[44:47], v[152:155], v[198:201], v[44:47]
	v_mfma_f32_16x16x32_bf16 v[40:43], v[144:147], v[206:209], v[40:43]
	v_mfma_f32_16x16x32_bf16 v[36:39], v[152:155], v[206:209], v[36:39]
	v_mfma_f32_16x16x32_bf16 v[64:67], v[148:151], v[186:189], v[64:67]
	v_mfma_f32_16x16x32_bf16 v[60:63], v[156:159], v[186:189], v[60:63]
	v_mfma_f32_16x16x32_bf16 v[56:59], v[148:151], v[194:197], v[56:59]
	v_mfma_f32_16x16x32_bf16 v[52:55], v[156:159], v[194:197], v[52:55]
	v_mfma_f32_16x16x32_bf16 v[48:51], v[148:151], v[202:205], v[48:51]
	v_mfma_f32_16x16x32_bf16 v[44:47], v[156:159], v[202:205], v[44:47]
	v_mfma_f32_16x16x32_bf16 v[40:43], v[148:151], v[220:223], v[40:43]
	v_mfma_f32_16x16x32_bf16 v[36:39], v[156:159], v[220:223], v[36:39]
	s_setprio 0
	s_setprio 1
	v_mfma_f32_16x16x32_bf16 v[32:35], v[160:163], v[182:185], v[32:35]
	v_mfma_f32_16x16x32_bf16 v[28:31], v[168:171], v[182:185], v[28:31]
	v_mfma_f32_16x16x32_bf16 v[24:27], v[160:163], v[190:193], v[24:27]
	v_mfma_f32_16x16x32_bf16 v[20:23], v[168:171], v[190:193], v[20:23]
	v_mfma_f32_16x16x32_bf16 v[16:19], v[160:163], v[198:201], v[16:19]
	v_mfma_f32_16x16x32_bf16 v[12:15], v[168:171], v[198:201], v[12:15]
	v_mfma_f32_16x16x32_bf16 v[8:11], v[160:163], v[206:209], v[8:11]
	v_mfma_f32_16x16x32_bf16 v[2:5], v[168:171], v[206:209], v[4:7]
	v_mfma_f32_16x16x32_bf16 v[32:35], v[164:167], v[186:189], v[32:35]
	v_mfma_f32_16x16x32_bf16 v[28:31], v[172:175], v[186:189], v[28:31]
	v_mfma_f32_16x16x32_bf16 v[24:27], v[164:167], v[194:197], v[24:27]
	v_mfma_f32_16x16x32_bf16 v[20:23], v[172:175], v[194:197], v[20:23]
	v_mfma_f32_16x16x32_bf16 v[16:19], v[164:167], v[202:205], v[16:19]
	v_mfma_f32_16x16x32_bf16 v[12:15], v[172:175], v[202:205], v[12:15]
	v_mfma_f32_16x16x32_bf16 v[8:11], v[164:167], v[220:223], v[8:11]
	v_mfma_f32_16x16x32_bf16 v[2:5], v[172:175], v[220:223], v[2:5]
	s_barrier
	s_setprio 0
	s_add_i32 s27, 0, 0x18000
	v_add_u32_e32 v0, s27, v179
	s_add_i32 s54, 0, 0x1c000
	ds_read_b128 v[144:147], v0
	ds_read_b128 v[148:151], v0 offset:1024
	ds_read_b128 v[152:155], v0 offset:2048
	ds_read_b128 v[156:159], v0 offset:3072
	v_add_u32_e32 v0, s54, v179
	ds_read_b128 v[160:163], v0
	ds_read_b128 v[164:167], v0 offset:1024
	ds_read_b128 v[168:171], v0 offset:2048
	ds_read_b128 v[172:175], v0 offset:3072
	s_add_u32 s30, s30, 0x20000
	s_addc_u32 s31, s31, 0
	s_mov_b32 m0, s41
	v_lshl_add_u64 v[6:7], s[30:31], 0, v[132:133]
	ds_read_b128 v[182:185], v181 offset:32768
	ds_read_b128 v[186:189], v181 offset:33792
	ds_read_b128 v[190:193], v181 offset:34816
	ds_read_b128 v[194:197], v181 offset:35840
	ds_read_b128 v[198:201], v181 offset:36864
	ds_read_b128 v[202:205], v181 offset:37888
	ds_read_b128 v[206:209], v181 offset:38912
	ds_read_b128 v[220:223], v181 offset:39936
	global_load_lds_dwordx4 v[6:7], off
	v_lshl_add_u64 v[6:7], s[30:31], 0, v[136:137]
	s_mov_b32 m0, s42
	s_nop 0
	global_load_lds_dwordx4 v[6:7], off
	s_waitcnt vmcnt(8)
	s_waitcnt lgkmcnt(0)
	s_setprio 1
	s_barrier
	s_waitcnt lgkmcnt(0)
	v_mfma_f32_16x16x32_bf16 v[128:131], v[144:147], v[182:185], v[128:131]
	v_mfma_f32_16x16x32_bf16 v[124:127], v[152:155], v[182:185], v[124:127]
	v_mfma_f32_16x16x32_bf16 v[120:123], v[144:147], v[190:193], v[120:123]
	v_mfma_f32_16x16x32_bf16 v[116:119], v[152:155], v[190:193], v[116:119]
	v_mfma_f32_16x16x32_bf16 v[112:115], v[144:147], v[198:201], v[112:115]
	v_mfma_f32_16x16x32_bf16 v[108:111], v[152:155], v[198:201], v[108:111]
	v_mfma_f32_16x16x32_bf16 v[104:107], v[144:147], v[206:209], v[104:107]
	v_mfma_f32_16x16x32_bf16 v[100:103], v[152:155], v[206:209], v[100:103]
	v_mfma_f32_16x16x32_bf16 v[128:131], v[148:151], v[186:189], v[128:131]
	v_mfma_f32_16x16x32_bf16 v[124:127], v[156:159], v[186:189], v[124:127]
	v_mfma_f32_16x16x32_bf16 v[120:123], v[148:151], v[194:197], v[120:123]
	v_mfma_f32_16x16x32_bf16 v[116:119], v[156:159], v[194:197], v[116:119]
	v_mfma_f32_16x16x32_bf16 v[112:115], v[148:151], v[202:205], v[112:115]
	v_mfma_f32_16x16x32_bf16 v[108:111], v[156:159], v[202:205], v[108:111]
	v_mfma_f32_16x16x32_bf16 v[104:107], v[148:151], v[220:223], v[104:107]
	v_mfma_f32_16x16x32_bf16 v[100:103], v[156:159], v[220:223], v[100:103]
	s_setprio 0
	s_setprio 1
	v_mfma_f32_16x16x32_bf16 v[96:99], v[160:163], v[182:185], v[96:99]
	v_mfma_f32_16x16x32_bf16 v[92:95], v[168:171], v[182:185], v[92:95]
	v_mfma_f32_16x16x32_bf16 v[88:91], v[160:163], v[190:193], v[88:91]
	v_mfma_f32_16x16x32_bf16 v[84:87], v[168:171], v[190:193], v[84:87]
	v_mfma_f32_16x16x32_bf16 v[80:83], v[160:163], v[198:201], v[80:83]
	v_mfma_f32_16x16x32_bf16 v[76:79], v[168:171], v[198:201], v[76:79]
	v_mfma_f32_16x16x32_bf16 v[72:75], v[160:163], v[206:209], v[72:75]
	v_mfma_f32_16x16x32_bf16 v[68:71], v[168:171], v[206:209], v[68:71]
	v_mfma_f32_16x16x32_bf16 v[96:99], v[164:167], v[186:189], v[96:99]
	v_mfma_f32_16x16x32_bf16 v[92:95], v[172:175], v[186:189], v[92:95]
	v_mfma_f32_16x16x32_bf16 v[88:91], v[164:167], v[194:197], v[88:91]
	v_mfma_f32_16x16x32_bf16 v[84:87], v[172:175], v[194:197], v[84:87]
	v_mfma_f32_16x16x32_bf16 v[80:83], v[164:167], v[202:205], v[80:83]
	v_mfma_f32_16x16x32_bf16 v[76:79], v[172:175], v[202:205], v[76:79]
	v_mfma_f32_16x16x32_bf16 v[72:75], v[164:167], v[220:223], v[72:75]
	v_mfma_f32_16x16x32_bf16 v[68:71], v[172:175], v[220:223], v[68:71]
	s_barrier
; #define PG8_STAGE(bufoff, gbase, voff) do { _Pragma("unroll") for (int _i = 0; _i < 2; ++_i) \
;         __builtin_amdgcn_global_load_lds((const unsigned*)((const char*)(gbase) + (voff)[_i]), (PG8_LAS unsigned*)(lds + (bufoff) + ldsw + _i * 8192), 16, 0, 0); } while (0)
; #define PG8_LDA(dst, b, h) do { _Pragma("unroll") for (int m = 0; m < 4; ++m) _Pragma("unroll") for (int k = 0; k < 2; ++k) dst[m][k] = *(const PG8_LAS bf16x8*)(lds + PG8_SA(b, h) + aoff + m * 2048 + k * 1024); } while (0)
; #define PG8_MMA(ai, bj, At, Bt) do { __builtin_amdgcn_s_setprio(1); _Pragma("unroll") for (int m = 0; m < 4; ++m) _Pragma("unroll") for (int n = 0; n < 2; ++n) _Pragma("unroll") for (int k = 0; k < 2; ++k) \
;         acc[ai][bj][m][n] = __builtin_amdgcn_mfma_f32_16x16x32_bf16(Bt[n][k], At[m][k], acc[ai][bj][m][n], 0, 0, 0); __builtin_amdgcn_s_setprio(0); } while (0)
; #define PG8_WAIT_V(n) asm volatile("s_waitcnt vmcnt(" #n ")" ::: "memory")
; #define PG8_WAIT_L(n) asm volatile("s_waitcnt lgkmcnt(" #n ")" ::: "memory")
; #define PG8_BAR __builtin_amdgcn_s_barrier()
; #define PG8_SCHED __builtin_amdgcn_sched_barrier(0)
; template <class Epi, class Sched, bool ALIGN_EPI = false, bool SP2 = false>
; __device__ __forceinline__ void gemm_phase(PG8_LAS unsigned char* lds, const Gemm g, const Sched& S, const Epi& E) {
;     ...
;             if (full) PG8_LDA(At, 1, 1); PG8_STAGE(PG8_SB(1, 0), b3, voffB); PG8_STAGE(PG8_SB(1, 1), b3 + hstep, voffB); PG8_STAGE(PG8_SA(1, 0), a3, voffA);
;             PG8_WAIT_V(8); PG8_WAIT_L(0); PG8_BAR; if (full) { PG8_MMA(1, 0, At, B0); PG8_MMA(1, 1, At, B1); } PG8_BAR; PG8_SCHED;
;     ...
;         if constexpr (ALIGN_EPI) { if (wr == 0) PG8_BAR; }
	s_setprio 0
	s_add_i32 s27, s27, s38
	v_lshl_add_u64 v[6:7], v[176:177], 0, s[52:53]
	s_mov_b32 m0, s27
	ds_read_b128 v[182:185], v181 offset:49152
	ds_read_b128 v[186:189], v181 offset:50176
	ds_read_b128 v[190:193], v181 offset:51200
	ds_read_b128 v[194:197], v181 offset:52224
	ds_read_b128 v[198:201], v181 offset:53248
	ds_read_b128 v[202:205], v181 offset:54272
	ds_read_b128 v[206:209], v181 offset:55296
	ds_read_b128 v[220:223], v181 offset:56320
	global_load_lds_dwordx4 v[6:7], off
	s_add_i32 m0, s27, 0x2000
	s_add_u32 s28, s28, 0x20080
	v_lshl_add_u64 v[6:7], v[210:211], 0, s[52:53]
	s_addc_u32 s29, s29, 0
	s_add_i32 s27, s54, s38
	global_load_lds_dwordx4 v[6:7], off
	v_lshl_add_u64 v[6:7], s[28:29], 0, v[134:135]
	s_mov_b32 m0, s27
	s_nop 0
	global_load_lds_dwordx4 v[6:7], off
	v_lshl_add_u64 v[6:7], s[28:29], 0, v[138:139]
	s_add_i32 m0, s27, 0x2000
	s_nop 0
	global_load_lds_dwordx4 v[6:7], off
	v_lshl_add_u64 v[6:7], v[212:213], 0, s[52:53]
	s_mov_b32 m0, s43
	s_nop 0
	global_load_lds_dwordx4 v[6:7], off
	v_lshl_add_u64 v[6:7], v[214:215], 0, s[52:53]
	s_mov_b32 m0, s44
	s_nop 0
	global_load_lds_dwordx4 v[6:7], off
	s_waitcnt vmcnt(8)
	s_waitcnt lgkmcnt(0)
	s_setprio 1
	s_barrier
	s_waitcnt lgkmcnt(0)
	v_mfma_f32_16x16x32_bf16 v[64:67], v[144:147], v[182:185], v[64:67]
	v_mfma_f32_16x16x32_bf16 v[60:63], v[152:155], v[182:185], v[60:63]
	v_mfma_f32_16x16x32_bf16 v[56:59], v[144:147], v[190:193], v[56:59]
	v_mfma_f32_16x16x32_bf16 v[52:55], v[152:155], v[190:193], v[52:55]
	v_mfma_f32_16x16x32_bf16 v[48:51], v[144:147], v[198:201], v[48:51]
	v_mfma_f32_16x16x32_bf16 v[44:47], v[152:155], v[198:201], v[44:47]
	v_mfma_f32_16x16x32_bf16 v[40:43], v[144:147], v[206:209], v[40:43]
	v_mfma_f32_16x16x32_bf16 v[36:39], v[152:155], v[206:209], v[36:39]
	v_mfma_f32_16x16x32_bf16 v[64:67], v[148:151], v[186:189], v[64:67]
	v_mfma_f32_16x16x32_bf16 v[60:63], v[156:159], v[186:189], v[60:63]
	v_mfma_f32_16x16x32_bf16 v[56:59], v[148:151], v[194:197], v[56:59]
	v_mfma_f32_16x16x32_bf16 v[52:55], v[156:159], v[194:197], v[52:55]
	v_mfma_f32_16x16x32_bf16 v[48:51], v[148:151], v[202:205], v[48:51]
	v_mfma_f32_16x16x32_bf16 v[44:47], v[156:159], v[202:205], v[44:47]
	v_mfma_f32_16x16x32_bf16 v[40:43], v[148:151], v[220:223], v[40:43]
	v_mfma_f32_16x16x32_bf16 v[36:39], v[156:159], v[220:223], v[36:39]
	s_setprio 0
	s_setprio 1
	v_mfma_f32_16x16x32_bf16 v[32:35], v[160:163], v[182:185], v[32:35]
	v_mfma_f32_16x16x32_bf16 v[28:31], v[168:171], v[182:185], v[28:31]
	v_mfma_f32_16x16x32_bf16 v[24:27], v[160:163], v[190:193], v[24:27]
	v_mfma_f32_16x16x32_bf16 v[20:23], v[168:171], v[190:193], v[20:23]
	v_mfma_f32_16x16x32_bf16 v[16:19], v[160:163], v[198:201], v[16:19]
	v_mfma_f32_16x16x32_bf16 v[12:15], v[168:171], v[198:201], v[12:15]
	v_mfma_f32_16x16x32_bf16 v[6:9], v[160:163], v[206:209], v[8:11]
	v_mfma_f32_16x16x32_bf16 v[2:5], v[168:171], v[206:209], v[2:5]
	v_mfma_f32_16x16x32_bf16 v[32:35], v[164:167], v[186:189], v[32:35]
	v_mfma_f32_16x16x32_bf16 v[28:31], v[172:175], v[186:189], v[28:31]
	v_mfma_f32_16x16x32_bf16 v[24:27], v[164:167], v[194:197], v[24:27]
	v_mfma_f32_16x16x32_bf16 v[20:23], v[172:175], v[194:197], v[20:23]
	v_mfma_f32_16x16x32_bf16 v[16:19], v[164:167], v[202:205], v[16:19]
	v_mfma_f32_16x16x32_bf16 v[12:15], v[172:175], v[202:205], v[12:15]
	v_mfma_f32_16x16x32_bf16 v[8:11], v[164:167], v[220:223], v[6:9]
	v_mfma_f32_16x16x32_bf16 v[4:7], v[172:175], v[220:223], v[2:5]
	s_barrier
	s_setprio 0
	s_add_i32 s25, s25, 2
	s_add_u32 s6, s6, 0x100
	s_addc_u32 s7, s7, 0
	s_add_u32 s17, s17, 0x100
	s_addc_u32 s19, s19, 0
	s_cmp_gt_u32 s25, 5
	s_cbranch_scc0 .LBB0_1038
	s_and_b64 vcc, exec, s[14:15]
	s_cbranch_vccz .LBB0_1041
	s_barrier

; #define PG8_STAGE(bufoff, gbase, voff) do { _Pragma("unroll") for (int _i = 0; _i < 2; ++_i) \
;         __builtin_amdgcn_global_load_lds((const unsigned*)((const char*)(gbase) + (voff)[_i]), (PG8_LAS unsigned*)(lds + (bufoff) + ldsw + _i * 8192), 16, 0, 0); } while (0)
; #define PG8_LDA(dst, b, h) do { _Pragma("unroll") for (int m = 0; m < 4; ++m) _Pragma("unroll") for (int k = 0; k < 2; ++k) dst[m][k] = *(const PG8_LAS bf16x8*)(lds + PG8_SA(b, h) + aoff + m * 2048 + k * 1024); } while (0)
; #define PG8_LDB(dst, b, h) do { _Pragma("unroll") for (int n = 0; n < 2; ++n) _Pragma("unroll") for (int k = 0; k < 2; ++k) dst[n][k] = *(const PG8_LAS bf16x8*)(lds + PG8_SB(b, h) + boff + n * 2048 + k * 1024); } while (0)
; #define PG8_MMA(ai, bj, At, Bt) do { __builtin_amdgcn_s_setprio(1); _Pragma("unroll") for (int m = 0; m < 4; ++m) _Pragma("unroll") for (int n = 0; n < 2; ++n) _Pragma("unroll") for (int k = 0; k < 2; ++k) \
;         acc[ai][bj][m][n] = __builtin_amdgcn_mfma_f32_16x16x32_bf16(Bt[n][k], At[m][k], acc[ai][bj][m][n], 0, 0, 0); __builtin_amdgcn_s_setprio(0); } while (0)
; #define PG8_WAIT_V(n) asm volatile("s_waitcnt vmcnt(" #n ")" ::: "memory")
; #define PG8_WAIT_L(n) asm volatile("s_waitcnt lgkmcnt(" #n ")" ::: "memory")
; #define PG8_BAR __builtin_amdgcn_s_barrier()
; #define PG8_SCHED __builtin_amdgcn_sched_barrier(0)
; template <class Epi, class Sched, bool ALIGN_EPI = false, bool SP2 = false>
; __device__ __forceinline__ void gemm_phase(PG8_LAS unsigned char* lds, const Gemm g, const Sched& S, const Epi& E) {
;     ...
;             const bool last = (t == nt - 2);
;             const char* a1 = cA + (size_t)(t + 1) * kstep;
;             const char* a2 = last ? nA : cA + (size_t)(t + 2) * kstep; const char* b2 = last ? nB : cB + (size_t)(t + 2) * kstep;
;             const char* a3 = a2 + kstep; const char* b3 = b2 + kstep;
;             if (last && has_next) S.a_ready(nxt);
;             if constexpr (SP2) {
;             PG8_LDB(B0, 0, 0); PG8_LDB(B1, 0, 1); PG8_SCHED; PG8_LDA(At, 0, 0); PG8_STAGE(PG8_SA(1, 1), a1 + hstep, voffA);
;             PG8_WAIT_V(8); PG8_WAIT_L(0); PG8_BAR; PG8_MMA(0, 0, At, B0); PG8_MMA(0, 1, At, B1); PG8_BAR; PG8_SCHED;
;             if (full) PG8_LDA(At, 0, 1); PG8_STAGE(PG8_SB(0, 0), b2, voffB); PG8_STAGE(PG8_SB(0, 1), b2 + hstep, voffB); PG8_STAGE(PG8_SA(0, 0), a2, voffA);
.LBB0_1149:
	s_add_u32 s30, s18, s28
	s_addc_u32 s31, s19, s29
	s_add_u32 s30, s30, 0x100
	s_addc_u32 s31, s31, 0
	s_add_u32 s62, s57, s28
	s_addc_u32 s63, s58, s29
	s_add_i32 s64, 0, 0x10000
	s_cmpk_eq_i32 s28, 0x700
	s_cselect_b32 s35, s23, s31
	s_cselect_b32 s34, s59, s30
	v_add_u32_e32 v143, s64, v140
	s_cselect_b32 s31, s21, s63
	s_cselect_b32 s30, s60, s62
	s_add_i32 s65, 0, 0x14000
	ds_read_b128 v[144:147], v143
	ds_read_b128 v[148:151], v143 offset:1024
	ds_read_b128 v[152:155], v143 offset:2048
	ds_read_b128 v[156:159], v143 offset:3072
	v_add_u32_e32 v143, s65, v140
	ds_read_b128 v[160:163], v143
	ds_read_b128 v[164:167], v143 offset:1024
	ds_read_b128 v[168:171], v143 offset:2048
	ds_read_b128 v[174:177], v143 offset:3072
	v_lshl_add_u64 v[210:211], v[136:137], 0, s[28:29]
	s_add_i32 m0, s41, 0xc000
	ds_read_b128 v[178:181], v141
	ds_read_b128 v[182:185], v141 offset:1024
	ds_read_b128 v[186:189], v141 offset:2048
	ds_read_b128 v[190:193], v141 offset:3072
	ds_read_b128 v[194:197], v141 offset:4096
	ds_read_b128 v[198:201], v141 offset:5120
	ds_read_b128 v[202:205], v141 offset:6144
	ds_read_b128 v[206:209], v141 offset:7168
	global_load_lds_dwordx4 v[210:211], off
	v_lshl_add_u64 v[210:211], v[138:139], 0, s[28:29]
	s_add_i32 m0, s41, 0xe000
	s_nop 0
	global_load_lds_dwordx4 v[210:211], off
	s_waitcnt vmcnt(8)
	s_waitcnt lgkmcnt(0)
	s_setprio 1
	s_barrier
	s_waitcnt lgkmcnt(0)
	v_mfma_f32_16x16x32_bf16 v[126:129], v[144:147], v[178:181], v[126:129]
	v_mfma_f32_16x16x32_bf16 v[86:89], v[152:155], v[178:181], v[86:89]
	v_mfma_f32_16x16x32_bf16 v[114:117], v[144:147], v[186:189], v[114:117]
	v_mfma_f32_16x16x32_bf16 v[82:85], v[152:155], v[186:189], v[82:85]
	v_mfma_f32_16x16x32_bf16 v[122:125], v[144:147], v[194:197], v[122:125]
	v_mfma_f32_16x16x32_bf16 v[106:109], v[152:155], v[194:197], v[106:109]
	v_mfma_f32_16x16x32_bf16 v[118:121], v[144:147], v[202:205], v[118:121]
	v_mfma_f32_16x16x32_bf16 v[110:113], v[152:155], v[202:205], v[110:113]
	v_mfma_f32_16x16x32_bf16 v[126:129], v[148:151], v[182:185], v[126:129]
	v_mfma_f32_16x16x32_bf16 v[86:89], v[156:159], v[182:185], v[86:89]
	v_mfma_f32_16x16x32_bf16 v[114:117], v[148:151], v[190:193], v[114:117]
	v_mfma_f32_16x16x32_bf16 v[82:85], v[156:159], v[190:193], v[82:85]
	v_mfma_f32_16x16x32_bf16 v[122:125], v[148:151], v[198:201], v[122:125]
	v_mfma_f32_16x16x32_bf16 v[106:109], v[156:159], v[198:201], v[106:109]
	v_mfma_f32_16x16x32_bf16 v[118:121], v[148:151], v[206:209], v[118:121]
	v_mfma_f32_16x16x32_bf16 v[110:113], v[156:159], v[206:209], v[110:113]
	s_setprio 0
	s_setprio 1
	v_mfma_f32_16x16x32_bf16 v[22:25], v[160:163], v[178:181], v[22:25]
	v_mfma_f32_16x16x32_bf16 v[6:9], v[168:171], v[178:181], v[6:9]
	v_mfma_f32_16x16x32_bf16 v[18:21], v[160:163], v[186:189], v[18:21]
	v_mfma_f32_16x16x32_bf16 v[2:5], v[168:171], v[186:189], v[2:5]
	v_mfma_f32_16x16x32_bf16 v[38:41], v[160:163], v[194:197], v[38:41]
	v_mfma_f32_16x16x32_bf16 v[10:13], v[168:171], v[194:197], v[10:13]
	v_mfma_f32_16x16x32_bf16 v[34:37], v[160:163], v[202:205], v[34:37]
	v_mfma_f32_16x16x32_bf16 v[14:17], v[168:171], v[202:205], v[14:17]
	v_mfma_f32_16x16x32_bf16 v[22:25], v[164:167], v[182:185], v[22:25]
	v_mfma_f32_16x16x32_bf16 v[6:9], v[174:177], v[182:185], v[6:9]
	v_mfma_f32_16x16x32_bf16 v[18:21], v[164:167], v[190:193], v[18:21]
	v_mfma_f32_16x16x32_bf16 v[2:5], v[174:177], v[190:193], v[2:5]
	v_mfma_f32_16x16x32_bf16 v[38:41], v[164:167], v[198:201], v[38:41]
	v_mfma_f32_16x16x32_bf16 v[10:13], v[174:177], v[198:201], v[10:13]
	v_mfma_f32_16x16x32_bf16 v[34:37], v[164:167], v[206:209], v[34:37]
	v_mfma_f32_16x16x32_bf16 v[14:17], v[174:177], v[206:209], v[14:17]
	s_barrier
	s_setprio 0
	s_add_i32 s62, s64, s40
	v_lshl_add_u64 v[210:211], s[30:31], 0, v[0:1]
	s_mov_b32 m0, s62
	ds_read_b128 v[178:181], v141 offset:16384
	ds_read_b128 v[182:185], v141 offset:17408
	ds_read_b128 v[186:189], v141 offset:18432
	ds_read_b128 v[190:193], v141 offset:19456
	ds_read_b128 v[194:197], v141 offset:20480
	ds_read_b128 v[198:201], v141 offset:21504
	ds_read_b128 v[202:205], v141 offset:22528
	ds_read_b128 v[206:209], v141 offset:23552
	global_load_lds_dwordx4 v[210:211], off
	s_add_i32 m0, s62, 0x2000
	s_add_u32 s62, s30, 0x40000
	v_lshl_add_u64 v[212:213], s[30:31], 0, v[130:131]
	s_addc_u32 s63, s31, 0
	s_add_i32 s64, s65, s40
	global_load_lds_dwordx4 v[212:213], off
	v_lshl_add_u64 v[214:215], s[62:63], 0, v[0:1]
	s_mov_b32 m0, s64
	v_lshl_add_u64 v[220:221], s[34:35], 0, v[130:131]
	global_load_lds_dwordx4 v[214:215], off
	v_lshl_add_u64 v[214:215], s[62:63], 0, v[130:131]
	s_add_i32 m0, s64, 0x2000
	s_nop 0
	global_load_lds_dwordx4 v[214:215], off
	v_lshl_add_u64 v[214:215], s[34:35], 0, v[0:1]
	s_mov_b32 m0, s41
	s_nop 0
	global_load_lds_dwordx4 v[214:215], off
	s_mov_b32 m0, s42
	s_nop 0
	global_load_lds_dwordx4 v[220:221], off
	s_waitcnt vmcnt(8)
	s_waitcnt lgkmcnt(0)
	s_setprio 1
	s_barrier
; #define PG8_STAGE(bufoff, gbase, voff) do { _Pragma("unroll") for (int _i = 0; _i < 2; ++_i) \
;         __builtin_amdgcn_global_load_lds((const unsigned*)((const char*)(gbase) + (voff)[_i]), (PG8_LAS unsigned*)(lds + (bufoff) + ldsw + _i * 8192), 16, 0, 0); } while (0)
; #define PG8_LDA(dst, b, h) do { _Pragma("unroll") for (int m = 0; m < 4; ++m) _Pragma("unroll") for (int k = 0; k < 2; ++k) dst[m][k] = *(const PG8_LAS bf16x8*)(lds + PG8_SA(b, h) + aoff + m * 2048 + k * 1024); } while (0)
; #define PG8_LDB(dst, b, h) do { _Pragma("unroll") for (int n = 0; n < 2; ++n) _Pragma("unroll") for (int k = 0; k < 2; ++k) dst[n][k] = *(const PG8_LAS bf16x8*)(lds + PG8_SB(b, h) + boff + n * 2048 + k * 1024); } while (0)
; #define PG8_MMA(ai, bj, At, Bt) do { __builtin_amdgcn_s_setprio(1); _Pragma("unroll") for (int m = 0; m < 4; ++m) _Pragma("unroll") for (int n = 0; n < 2; ++n) _Pragma("unroll") for (int k = 0; k < 2; ++k) \
;         acc[ai][bj][m][n] = __builtin_amdgcn_mfma_f32_16x16x32_bf16(Bt[n][k], At[m][k], acc[ai][bj][m][n], 0, 0, 0); __builtin_amdgcn_s_setprio(0); } while (0)
; #define PG8_WAIT_V(n) asm volatile("s_waitcnt vmcnt(" #n ")" ::: "memory")
; #define PG8_WAIT_L(n) asm volatile("s_waitcnt lgkmcnt(" #n ")" ::: "memory")
; #define PG8_BAR __builtin_amdgcn_s_barrier()
; #define PG8_SCHED __builtin_amdgcn_sched_barrier(0)
; template <class Epi, class Sched, bool ALIGN_EPI = false, bool SP2 = false>
; __device__ __forceinline__ void gemm_phase(PG8_LAS unsigned char* lds, const Gemm g, const Sched& S, const Epi& E) {
;     ...
;             PG8_WAIT_V(8); PG8_WAIT_L(0); PG8_BAR; if (full) { PG8_MMA(1, 0, At, B0); PG8_MMA(1, 1, At, B1); } PG8_BAR; PG8_SCHED;
;             PG8_LDB(B0, 1, 0); PG8_LDB(B1, 1, 1); PG8_SCHED; PG8_LDA(At, 1, 0); PG8_STAGE(PG8_SA(0, 1), a2 + hstep, voffA);
;             PG8_WAIT_V(8); PG8_WAIT_L(0); PG8_BAR; PG8_MMA(0, 0, At, B0); PG8_MMA(0, 1, At, B1); PG8_BAR; PG8_SCHED;
	s_waitcnt lgkmcnt(0)
	v_mfma_f32_16x16x32_bf16 v[102:105], v[144:147], v[178:181], v[102:105]
	v_mfma_f32_16x16x32_bf16 v[98:101], v[152:155], v[178:181], v[98:101]
	v_mfma_f32_16x16x32_bf16 v[94:97], v[144:147], v[186:189], v[94:97]
	v_mfma_f32_16x16x32_bf16 v[90:93], v[152:155], v[186:189], v[90:93]
	v_mfma_f32_16x16x32_bf16 v[78:81], v[144:147], v[194:197], v[78:81]
	v_mfma_f32_16x16x32_bf16 v[74:77], v[152:155], v[194:197], v[74:77]
	v_mfma_f32_16x16x32_bf16 v[70:73], v[144:147], v[202:205], v[70:73]
	v_mfma_f32_16x16x32_bf16 v[66:69], v[152:155], v[202:205], v[66:69]
	v_mfma_f32_16x16x32_bf16 v[102:105], v[148:151], v[182:185], v[102:105]
	v_mfma_f32_16x16x32_bf16 v[98:101], v[156:159], v[182:185], v[98:101]
	v_mfma_f32_16x16x32_bf16 v[94:97], v[148:151], v[190:193], v[94:97]
	v_mfma_f32_16x16x32_bf16 v[90:93], v[156:159], v[190:193], v[90:93]
	v_mfma_f32_16x16x32_bf16 v[78:81], v[148:151], v[198:201], v[78:81]
	v_mfma_f32_16x16x32_bf16 v[74:77], v[156:159], v[198:201], v[74:77]
	v_mfma_f32_16x16x32_bf16 v[70:73], v[148:151], v[206:209], v[70:73]
	v_mfma_f32_16x16x32_bf16 v[66:69], v[156:159], v[206:209], v[66:69]
	s_setprio 0
	s_setprio 1
	v_mfma_f32_16x16x32_bf16 v[50:53], v[160:163], v[178:181], v[50:53]
	v_mfma_f32_16x16x32_bf16 v[26:29], v[168:171], v[178:181], v[26:29]
	v_mfma_f32_16x16x32_bf16 v[46:49], v[160:163], v[186:189], v[46:49]
	v_mfma_f32_16x16x32_bf16 v[30:33], v[168:171], v[186:189], v[30:33]
	v_mfma_f32_16x16x32_bf16 v[62:65], v[160:163], v[194:197], v[62:65]
	v_mfma_f32_16x16x32_bf16 v[54:57], v[168:171], v[194:197], v[54:57]
	v_mfma_f32_16x16x32_bf16 v[58:61], v[160:163], v[202:205], v[58:61]
	v_mfma_f32_16x16x32_bf16 v[42:45], v[168:171], v[202:205], v[42:45]
	v_mfma_f32_16x16x32_bf16 v[50:53], v[164:167], v[182:185], v[50:53]
	v_mfma_f32_16x16x32_bf16 v[26:29], v[174:177], v[182:185], v[26:29]
	v_mfma_f32_16x16x32_bf16 v[46:49], v[164:167], v[190:193], v[46:49]
	v_mfma_f32_16x16x32_bf16 v[30:33], v[174:177], v[190:193], v[30:33]
	v_mfma_f32_16x16x32_bf16 v[62:65], v[164:167], v[198:201], v[62:65]
	v_mfma_f32_16x16x32_bf16 v[54:57], v[174:177], v[198:201], v[54:57]
	v_mfma_f32_16x16x32_bf16 v[58:61], v[164:167], v[206:209], v[58:61]
	v_mfma_f32_16x16x32_bf16 v[42:45], v[174:177], v[206:209], v[42:45]
	s_barrier
	s_setprio 0
	s_add_i32 s62, 0, 0x18000
	v_add_u32_e32 v143, s62, v140
	s_add_i32 s63, 0, 0x1c000
	ds_read_b128 v[144:147], v143
	ds_read_b128 v[148:151], v143 offset:1024
	ds_read_b128 v[152:155], v143 offset:2048
	ds_read_b128 v[156:159], v143 offset:3072
	v_add_u32_e32 v143, s63, v140
	ds_read_b128 v[160:163], v143
	ds_read_b128 v[164:167], v143 offset:1024
	ds_read_b128 v[168:171], v143 offset:2048
	ds_read_b128 v[174:177], v143 offset:3072
	s_add_u32 s34, s34, 0x40000
	s_addc_u32 s35, s35, 0
	s_mov_b32 m0, s43
	v_lshl_add_u64 v[222:223], s[34:35], 0, v[0:1]
	ds_read_b128 v[178:181], v141 offset:32768
	ds_read_b128 v[182:185], v141 offset:33792
	ds_read_b128 v[186:189], v141 offset:34816
	ds_read_b128 v[190:193], v141 offset:35840
	ds_read_b128 v[194:197], v141 offset:36864
	ds_read_b128 v[198:201], v141 offset:37888
	ds_read_b128 v[202:205], v141 offset:38912
	ds_read_b128 v[206:209], v141 offset:39936
	global_load_lds_dwordx4 v[222:223], off
	v_lshl_add_u64 v[222:223], s[34:35], 0, v[130:131]
	s_mov_b32 m0, s44
	s_nop 0
	global_load_lds_dwordx4 v[222:223], off
	s_waitcnt vmcnt(8)
	s_waitcnt lgkmcnt(0)
	s_setprio 1
	s_barrier
	s_waitcnt lgkmcnt(0)
	v_mfma_f32_16x16x32_bf16 v[126:129], v[144:147], v[178:181], v[126:129]
	v_mfma_f32_16x16x32_bf16 v[86:89], v[152:155], v[178:181], v[86:89]
	v_mfma_f32_16x16x32_bf16 v[114:117], v[144:147], v[186:189], v[114:117]
	v_mfma_f32_16x16x32_bf16 v[82:85], v[152:155], v[186:189], v[82:85]
	v_mfma_f32_16x16x32_bf16 v[122:125], v[144:147], v[194:197], v[122:125]
	v_mfma_f32_16x16x32_bf16 v[106:109], v[152:155], v[194:197], v[106:109]
	v_mfma_f32_16x16x32_bf16 v[118:121], v[144:147], v[202:205], v[118:121]
	v_mfma_f32_16x16x32_bf16 v[110:113], v[152:155], v[202:205], v[110:113]
	v_mfma_f32_16x16x32_bf16 v[126:129], v[148:151], v[182:185], v[126:129]
	v_mfma_f32_16x16x32_bf16 v[86:89], v[156:159], v[182:185], v[86:89]
	v_mfma_f32_16x16x32_bf16 v[114:117], v[148:151], v[190:193], v[114:117]
	v_mfma_f32_16x16x32_bf16 v[82:85], v[156:159], v[190:193], v[82:85]
	v_mfma_f32_16x16x32_bf16 v[122:125], v[148:151], v[198:201], v[122:125]
	v_mfma_f32_16x16x32_bf16 v[106:109], v[156:159], v[198:201], v[106:109]
	v_mfma_f32_16x16x32_bf16 v[118:121], v[148:151], v[206:209], v[118:121]
	v_mfma_f32_16x16x32_bf16 v[110:113], v[156:159], v[206:209], v[110:113]
	s_setprio 0
	s_setprio 1
	v_mfma_f32_16x16x32_bf16 v[22:25], v[160:163], v[178:181], v[22:25]
	v_mfma_f32_16x16x32_bf16 v[6:9], v[168:171], v[178:181], v[6:9]
	v_mfma_f32_16x16x32_bf16 v[18:21], v[160:163], v[186:189], v[18:21]
	v_mfma_f32_16x16x32_bf16 v[2:5], v[168:171], v[186:189], v[2:5]
	v_mfma_f32_16x16x32_bf16 v[38:41], v[160:163], v[194:197], v[38:41]
	v_mfma_f32_16x16x32_bf16 v[10:13], v[168:171], v[194:197], v[10:13]
	v_mfma_f32_16x16x32_bf16 v[34:37], v[160:163], v[202:205], v[34:37]
	v_mfma_f32_16x16x32_bf16 v[14:17], v[168:171], v[202:205], v[14:17]
	v_mfma_f32_16x16x32_bf16 v[22:25], v[164:167], v[182:185], v[22:25]
	v_mfma_f32_16x16x32_bf16 v[6:9], v[174:177], v[182:185], v[6:9]
	v_mfma_f32_16x16x32_bf16 v[18:21], v[164:167], v[190:193], v[18:21]
	v_mfma_f32_16x16x32_bf16 v[2:5], v[174:177], v[190:193], v[2:5]
	v_mfma_f32_16x16x32_bf16 v[38:41], v[164:167], v[198:201], v[38:41]
	v_mfma_f32_16x16x32_bf16 v[10:13], v[174:177], v[198:201], v[10:13]
	v_mfma_f32_16x16x32_bf16 v[34:37], v[164:167], v[206:209], v[34:37]
	v_mfma_f32_16x16x32_bf16 v[14:17], v[174:177], v[206:209], v[14:17]
	s_barrier
; #define PG8_STAGE(bufoff, gbase, voff) do { _Pragma("unroll") for (int _i = 0; _i < 2; ++_i) \
;         __builtin_amdgcn_global_load_lds((const unsigned*)((const char*)(gbase) + (voff)[_i]), (PG8_LAS unsigned*)(lds + (bufoff) + ldsw + _i * 8192), 16, 0, 0); } while (0)
; #define PG8_LDA(dst, b, h) do { _Pragma("unroll") for (int m = 0; m < 4; ++m) _Pragma("unroll") for (int k = 0; k < 2; ++k) dst[m][k] = *(const PG8_LAS bf16x8*)(lds + PG8_SA(b, h) + aoff + m * 2048 + k * 1024); } while (0)
; #define PG8_MMA(ai, bj, At, Bt) do { __builtin_amdgcn_s_setprio(1); _Pragma("unroll") for (int m = 0; m < 4; ++m) _Pragma("unroll") for (int n = 0; n < 2; ++n) _Pragma("unroll") for (int k = 0; k < 2; ++k) \
;         acc[ai][bj][m][n] = __builtin_amdgcn_mfma_f32_16x16x32_bf16(Bt[n][k], At[m][k], acc[ai][bj][m][n], 0, 0, 0); __builtin_amdgcn_s_setprio(0); } while (0)
; #define PG8_WAIT_V(n) asm volatile("s_waitcnt vmcnt(" #n ")" ::: "memory")
; #define PG8_WAIT_L(n) asm volatile("s_waitcnt lgkmcnt(" #n ")" ::: "memory")
; #define PG8_BAR __builtin_amdgcn_s_barrier()
; #define PG8_SCHED __builtin_amdgcn_sched_barrier(0)
; template <class Epi, class Sched, bool ALIGN_EPI = false, bool SP2 = false>
; __device__ __forceinline__ void gemm_phase(PG8_LAS unsigned char* lds, const Gemm g, const Sched& S, const Epi& E) {
;     ...
;             if (full) PG8_LDA(At, 1, 1); PG8_STAGE(PG8_SB(1, 0), b3, voffB); PG8_STAGE(PG8_SB(1, 1), b3 + hstep, voffB); PG8_STAGE(PG8_SA(1, 0), a3, voffA);
;             PG8_WAIT_V(8); PG8_WAIT_L(0); PG8_BAR; if (full) { PG8_MMA(1, 0, At, B0); PG8_MMA(1, 1, At, B1); } PG8_BAR; PG8_SCHED;
;     ...
;         if (!has_next) break;
;         if (!Sched::KEEP || (nxt.pn >> 2) == 0) {
; #pragma unroll
;         for (int a = 0; a < 2; ++a)
; #pragma unroll
;             for (int b = 0; b < 2; ++b)
; #pragma unroll
;                 for (int m = 0; m < 4; ++m)
; #pragma unroll
;                     for (int n = 0; n < 2; ++n) acc[a][b][m][n] = (f32x4){0.f, 0.f, 0.f, 0.f};
;         }
	s_setprio 0
	s_add_i32 s34, s62, s40
	v_lshl_add_u64 v[210:211], v[210:211], 0, s[52:53]
	s_mov_b32 m0, s34
	ds_read_b128 v[178:181], v141 offset:49152
	ds_read_b128 v[182:185], v141 offset:50176
	ds_read_b128 v[186:189], v141 offset:51200
	ds_read_b128 v[190:193], v141 offset:52224
	ds_read_b128 v[194:197], v141 offset:53248
	ds_read_b128 v[198:201], v141 offset:54272
	ds_read_b128 v[202:205], v141 offset:55296
	ds_read_b128 v[206:209], v141 offset:56320
	global_load_lds_dwordx4 v[210:211], off
	s_add_i32 m0, s34, 0x2000
	s_add_u32 s30, s30, 0x40080
	v_lshl_add_u64 v[210:211], v[212:213], 0, s[52:53]
	s_addc_u32 s31, s31, 0
	s_add_i32 s34, s63, s40
	global_load_lds_dwordx4 v[210:211], off
	v_lshl_add_u64 v[210:211], s[30:31], 0, v[0:1]
	s_mov_b32 m0, s34
	s_nop 0
	global_load_lds_dwordx4 v[210:211], off
	v_lshl_add_u64 v[210:211], s[30:31], 0, v[130:131]
	s_add_i32 m0, s34, 0x2000
	s_nop 0
	global_load_lds_dwordx4 v[210:211], off
	v_lshl_add_u64 v[210:211], v[214:215], 0, s[52:53]
	s_mov_b32 m0, s48
	s_nop 0
	global_load_lds_dwordx4 v[210:211], off
	v_lshl_add_u64 v[210:211], v[220:221], 0, s[52:53]
	s_mov_b32 m0, s49
	s_nop 0
	global_load_lds_dwordx4 v[210:211], off
	s_waitcnt vmcnt(8)
	s_waitcnt lgkmcnt(0)
	s_setprio 1
	s_barrier
	s_waitcnt lgkmcnt(0)
	v_mfma_f32_16x16x32_bf16 v[102:105], v[144:147], v[178:181], v[102:105]
	v_mfma_f32_16x16x32_bf16 v[98:101], v[152:155], v[178:181], v[98:101]
	v_mfma_f32_16x16x32_bf16 v[94:97], v[144:147], v[186:189], v[94:97]
	v_mfma_f32_16x16x32_bf16 v[90:93], v[152:155], v[186:189], v[90:93]
	v_mfma_f32_16x16x32_bf16 v[78:81], v[144:147], v[194:197], v[78:81]
	v_mfma_f32_16x16x32_bf16 v[74:77], v[152:155], v[194:197], v[74:77]
	v_mfma_f32_16x16x32_bf16 v[70:73], v[144:147], v[202:205], v[70:73]
	v_mfma_f32_16x16x32_bf16 v[66:69], v[152:155], v[202:205], v[66:69]
	v_mfma_f32_16x16x32_bf16 v[102:105], v[148:151], v[182:185], v[102:105]
	v_mfma_f32_16x16x32_bf16 v[98:101], v[156:159], v[182:185], v[98:101]
	v_mfma_f32_16x16x32_bf16 v[94:97], v[148:151], v[190:193], v[94:97]
	v_mfma_f32_16x16x32_bf16 v[90:93], v[156:159], v[190:193], v[90:93]
	v_mfma_f32_16x16x32_bf16 v[78:81], v[148:151], v[198:201], v[78:81]
	v_mfma_f32_16x16x32_bf16 v[74:77], v[156:159], v[198:201], v[74:77]
	v_mfma_f32_16x16x32_bf16 v[70:73], v[148:151], v[206:209], v[70:73]
	v_mfma_f32_16x16x32_bf16 v[66:69], v[156:159], v[206:209], v[66:69]
	s_setprio 0
	s_setprio 1
	v_mfma_f32_16x16x32_bf16 v[50:53], v[160:163], v[178:181], v[50:53]
	v_mfma_f32_16x16x32_bf16 v[26:29], v[168:171], v[178:181], v[26:29]
	v_mfma_f32_16x16x32_bf16 v[46:49], v[160:163], v[186:189], v[46:49]
	v_mfma_f32_16x16x32_bf16 v[30:33], v[168:171], v[186:189], v[30:33]
	v_mfma_f32_16x16x32_bf16 v[62:65], v[160:163], v[194:197], v[62:65]
	v_mfma_f32_16x16x32_bf16 v[54:57], v[168:171], v[194:197], v[54:57]
	v_mfma_f32_16x16x32_bf16 v[58:61], v[160:163], v[202:205], v[58:61]
	v_mfma_f32_16x16x32_bf16 v[42:45], v[168:171], v[202:205], v[42:45]
	v_mfma_f32_16x16x32_bf16 v[50:53], v[164:167], v[182:185], v[50:53]
	v_mfma_f32_16x16x32_bf16 v[26:29], v[174:177], v[182:185], v[26:29]
	v_mfma_f32_16x16x32_bf16 v[46:49], v[164:167], v[190:193], v[46:49]
	v_mfma_f32_16x16x32_bf16 v[30:33], v[174:177], v[190:193], v[30:33]
	v_mfma_f32_16x16x32_bf16 v[62:65], v[164:167], v[198:201], v[62:65]
	v_mfma_f32_16x16x32_bf16 v[54:57], v[174:177], v[198:201], v[54:57]
	v_mfma_f32_16x16x32_bf16 v[58:61], v[164:167], v[206:209], v[58:61]
	v_mfma_f32_16x16x32_bf16 v[42:45], v[174:177], v[206:209], v[42:45]
	s_barrier
	s_setprio 0
	s_add_i32 s61, s61, 2
	s_add_u32 s28, s28, 0x100
	s_addc_u32 s29, s29, 0
	s_cmp_gt_u32 s61, 13
	s_cbranch_scc0 .LBB0_1149
	s_add_u32 s28, s57, 0xffffff00
	s_addc_u32 s29, s58, -1
	s_andn2_b64 vcc, exec, s[6:7]
	s_cbranch_vccnz .LBB0_1152
	v_mov_b32_e32 v42, 0
	s_mov_b32 s14, s20
	s_mov_b32 s12, s22
	s_mov_b64 s[18:19], s[26:27]
	s_mov_b32 s55, s56
	v_mov_b32_e32 v43, v42
	v_mov_b32_e32 v44, v42
	v_mov_b32_e32 v45, v42
	v_mov_b32_e32 v58, v42
	v_mov_b32_e32 v59, v42
	v_mov_b32_e32 v60, v42
	v_mov_b32_e32 v61, v42
	v_mov_b32_e32 v54, v42
	v_mov_b32_e32 v55, v42
	v_mov_b32_e32 v56, v42
	v_mov_b32_e32 v57, v42
	v_mov_b32_e32 v62, v42
	v_mov_b32_e32 v63, v42
	v_mov_b32_e32 v64, v42
	v_mov_b32_e32 v65, v42
	v_mov_b32_e32 v30, v42
	v_mov_b32_e32 v31, v42
	v_mov_b32_e32 v32, v42
	v_mov_b32_e32 v33, v42
	v_mov_b32_e32 v46, v42
	v_mov_b32_e32 v47, v42
	v_mov_b32_e32 v48, v42
	v_mov_b32_e32 v49, v42
	v_mov_b32_e32 v26, v42
	v_mov_b32_e32 v27, v42
	v_mov_b32_e32 v28, v42
	v_mov_b32_e32 v29, v42
	v_mov_b32_e32 v50, v42
	v_mov_b32_e32 v51, v42
	v_mov_b32_e32 v52, v42
	v_mov_b32_e32 v53, v42
	v_mov_b32_e32 v66, v42
	v_mov_b32_e32 v67, v42
	v_mov_b32_e32 v68, v42
	v_mov_b32_e32 v69, v42
	v_mov_b32_e32 v70, v42
	v_mov_b32_e32 v71, v42
	v_mov_b32_e32 v72, v42
	v_mov_b32_e32 v73, v42
	v_mov_b32_e32 v74, v42
	v_mov_b32_e32 v75, v42
	v_mov_b32_e32 v76, v42
	v_mov_b32_e32 v77, v42
	v_mov_b32_e32 v78, v42
	v_mov_b32_e32 v79, v42
	v_mov_b32_e32 v80, v42
	v_mov_b32_e32 v81, v42
	v_mov_b32_e32 v90, v42
	v_mov_b32_e32 v91, v42
	v_mov_b32_e32 v92, v42
	v_mov_b32_e32 v93, v42
	v_mov_b32_e32 v94, v42
	v_mov_b32_e32 v95, v42
	v_mov_b32_e32 v96, v42
	v_mov_b32_e32 v97, v42
	v_mov_b32_e32 v98, v42
	v_mov_b32_e32 v99, v42
	v_mov_b32_e32 v100, v42
	v_mov_b32_e32 v101, v42
	v_mov_b32_e32 v102, v42
	v_mov_b32_e32 v103, v42
	v_mov_b32_e32 v104, v42
	v_mov_b32_e32 v105, v42
	v_mov_b32_e32 v14, v42
	v_mov_b32_e32 v15, v42
	v_mov_b32_e32 v16, v42
	v_mov_b32_e32 v17, v42
	v_mov_b32_e32 v34, v42
	v_mov_b32_e32 v35, v42
	v_mov_b32_e32 v36, v42
	v_mov_b32_e32 v37, v42
	v_mov_b32_e32 v10, v42
	v_mov_b32_e32 v11, v42
	v_mov_b32_e32 v12, v42
	v_mov_b32_e32 v13, v42
	v_mov_b32_e32 v38, v42
	v_mov_b32_e32 v39, v42
	v_mov_b32_e32 v40, v42
	v_mov_b32_e32 v41, v42
	v_mov_b32_e32 v2, v42
	v_mov_b32_e32 v3, v42
	v_mov_b32_e32 v4, v42
	v_mov_b32_e32 v5, v42
	v_mov_b32_e32 v18, v42
	v_mov_b32_e32 v19, v42
	v_mov_b32_e32 v20, v42
	v_mov_b32_e32 v21, v42
	v_mov_b32_e32 v6, v42
	v_mov_b32_e32 v7, v42
	v_mov_b32_e32 v8, v42
	v_mov_b32_e32 v9, v42
	v_mov_b32_e32 v22, v42
	v_mov_b32_e32 v23, v42
	v_mov_b32_e32 v24, v42
	v_mov_b32_e32 v25, v42
	v_mov_b32_e32 v110, v42
	v_mov_b32_e32 v111, v42
	v_mov_b32_e32 v112, v42
	v_mov_b32_e32 v113, v42
	v_mov_b32_e32 v118, v42
	v_mov_b32_e32 v119, v42
	v_mov_b32_e32 v120, v42
	v_mov_b32_e32 v121, v42
	v_mov_b32_e32 v106, v42
	v_mov_b32_e32 v107, v42
	v_mov_b32_e32 v108, v42
	v_mov_b32_e32 v109, v42
	v_mov_b32_e32 v122, v42
	v_mov_b32_e32 v123, v42
	v_mov_b32_e32 v124, v42
	v_mov_b32_e32 v125, v42
	v_mov_b32_e32 v82, v42
	v_mov_b32_e32 v83, v42
	v_mov_b32_e32 v84, v42
	v_mov_b32_e32 v85, v42
	v_mov_b32_e32 v114, v42
	v_mov_b32_e32 v115, v42
	v_mov_b32_e32 v116, v42
	v_mov_b32_e32 v117, v42
	v_mov_b32_e32 v86, v42
	v_mov_b32_e32 v87, v42
	v_mov_b32_e32 v88, v42
	v_mov_b32_e32 v89, v42
	v_mov_b32_e32 v126, v42
	v_mov_b32_e32 v127, v42
	v_mov_b32_e32 v128, v42
	v_mov_b32_e32 v129, v42
	s_branch .LBB0_1153
